# K-loop: no s_setprio, merged closing waits, redundant post-barrier lgkmcnt removed, lane-mask complement via one SALU op
# speedup vs baseline: 1.0375x; 1.0049x over previous
.LBB0_176:
	s_mov_b32 m0, s55
	s_nop 0
	global_load_lds_dwordx4 v194, s[100:101]
	s_mov_b32 m0, s67
	s_nop 0
	global_load_lds_dwordx4 v196, s[100:101]
	v_add_u32_e32 v130, 0x10000, v243
	v_add_u32_e32 v142, 0x14000, v243
	ds_read_b128 v[146:149], v130
	ds_read_b128 v[150:153], v130 offset:1024
	ds_read_b128 v[154:157], v130 offset:2048
	ds_read_b128 v[158:161], v130 offset:3072
	ds_read_b128 v[130:133], v142
	ds_read_b128 v[134:137], v142 offset:1024
	ds_read_b128 v[138:141], v142 offset:2048
	ds_read_b128 v[142:145], v142 offset:3072
	v_lshl_add_u64 v[246:247], v[234:235], 0, s[80:81]
	s_add_i32 m0, s8, 0xc000
	s_waitcnt lgkmcnt(0)
	ds_read_b128 v[174:177], v244
	ds_read_b128 v[190:193], v244 offset:1024
	ds_read_b128 v[170:173], v244 offset:2048
	ds_read_b128 v[186:189], v244 offset:3072
	ds_read_b128 v[166:169], v244 offset:4096
	ds_read_b128 v[182:185], v244 offset:5120
	ds_read_b128 v[162:165], v244 offset:6144
	ds_read_b128 v[178:181], v244 offset:7168
	global_load_lds_dwordx4 v[246:247], off
	v_lshl_add_u64 v[246:247], v[236:237], 0, s[80:81]
	s_add_i32 m0, s8, 0xe000
	s_nop 0
	global_load_lds_dwordx4 v[246:247], off
	s_waitcnt vmcnt(8) lgkmcnt(0)
	s_barrier
	v_mfma_f32_16x16x32_bf16 v[118:121], v[146:149], v[174:177], v[118:121]
	v_mfma_f32_16x16x32_bf16 v[126:129], v[154:157], v[174:177], v[126:129]
	v_mfma_f32_16x16x32_bf16 v[102:105], v[146:149], v[170:173], v[102:105]
	v_mfma_f32_16x16x32_bf16 v[110:113], v[154:157], v[170:173], v[110:113]
	v_mfma_f32_16x16x32_bf16 v[86:89], v[146:149], v[166:169], v[86:89]
	v_mfma_f32_16x16x32_bf16 v[94:97], v[154:157], v[166:169], v[94:97]
	v_mfma_f32_16x16x32_bf16 v[70:73], v[146:149], v[162:165], v[70:73]
	v_mfma_f32_16x16x32_bf16 v[78:81], v[154:157], v[162:165], v[78:81]
	v_mfma_f32_16x16x32_bf16 v[118:121], v[150:153], v[190:193], v[118:121]
	v_mfma_f32_16x16x32_bf16 v[126:129], v[158:161], v[190:193], v[126:129]
	v_mfma_f32_16x16x32_bf16 v[102:105], v[150:153], v[186:189], v[102:105]
	v_mfma_f32_16x16x32_bf16 v[110:113], v[158:161], v[186:189], v[110:113]
	v_mfma_f32_16x16x32_bf16 v[86:89], v[150:153], v[182:185], v[86:89]
	v_mfma_f32_16x16x32_bf16 v[94:97], v[158:161], v[182:185], v[94:97]
	v_mfma_f32_16x16x32_bf16 v[70:73], v[150:153], v[178:181], v[70:73]
	v_mfma_f32_16x16x32_bf16 v[78:81], v[158:161], v[178:181], v[78:81]
	v_mfma_f32_16x16x32_bf16 v[122:125], v[130:133], v[174:177], v[122:125]
	v_mfma_f32_16x16x32_bf16 v[114:117], v[138:141], v[174:177], v[114:117]
	v_mfma_f32_16x16x32_bf16 v[106:109], v[130:133], v[170:173], v[106:109]
	v_mfma_f32_16x16x32_bf16 v[98:101], v[138:141], v[170:173], v[98:101]
	v_mfma_f32_16x16x32_bf16 v[90:93], v[130:133], v[166:169], v[90:93]
	v_mfma_f32_16x16x32_bf16 v[82:85], v[138:141], v[166:169], v[82:85]
	v_mfma_f32_16x16x32_bf16 v[74:77], v[130:133], v[162:165], v[74:77]
	v_mfma_f32_16x16x32_bf16 v[66:69], v[138:141], v[162:165], v[66:69]
	v_mfma_f32_16x16x32_bf16 v[122:125], v[134:137], v[190:193], v[122:125]
	v_mfma_f32_16x16x32_bf16 v[114:117], v[142:145], v[190:193], v[114:117]
	v_mfma_f32_16x16x32_bf16 v[106:109], v[134:137], v[186:189], v[106:109]
	v_mfma_f32_16x16x32_bf16 v[98:101], v[142:145], v[186:189], v[98:101]
	v_mfma_f32_16x16x32_bf16 v[90:93], v[134:137], v[182:185], v[90:93]
	v_mfma_f32_16x16x32_bf16 v[82:85], v[142:145], v[182:185], v[82:85]
	v_mfma_f32_16x16x32_bf16 v[74:77], v[134:137], v[178:181], v[74:77]
	v_mfma_f32_16x16x32_bf16 v[66:69], v[142:145], v[178:181], v[66:69]
	s_barrier
	s_andn2_b64 s[48:49], exec, s[50:51]
	s_andn2_b64 vcc, exec, s[50:51]
	s_cbranch_vccnz .LBB0_178
	ds_read_b128 v[174:177], v244 offset:16384
	ds_read_b128 v[190:193], v244 offset:17408
	ds_read_b128 v[170:173], v244 offset:18432
	ds_read_b128 v[186:189], v244 offset:19456
	ds_read_b128 v[166:169], v244 offset:20480
	ds_read_b128 v[182:185], v244 offset:21504
	ds_read_b128 v[162:165], v244 offset:22528
	ds_read_b128 v[178:181], v244 offset:23552
.LBB0_178:
	s_add_u32 s82, s0, s80
	s_addc_u32 s83, s1, s81
	s_add_u32 s84, s82, 0x460000
	s_addc_u32 s85, s83, 0
	s_cmp_eq_u32 s80, 0x41a0000
	s_cselect_b64 s[86:87], -1, 0
	s_and_b64 s[82:83], s[86:87], exec
	s_cselect_b32 s83, s71, s97
	s_cselect_b32 s82, s73, s79
	s_mov_b32 m0, s9
	s_cselect_b32 s85, s22, s85
	s_cselect_b32 s84, s69, s84
	s_add_u32 vcc_lo, s82, 0x4000
	global_load_lds_dwordx4 v194, s[82:83]
	s_mov_b32 m0, s10
	s_addc_u32 vcc_hi, s83, 0
	global_load_lds_dwordx4 v196, s[82:83]
	s_mov_b32 m0, s11
	s_nop 0
	global_load_lds_dwordx4 v194, vcc
	v_lshl_add_u64 v[246:247], vcc, 0, v[196:197]
	s_mov_b32 m0, s12
	s_and_b64 vcc, exec, s[48:49]
	global_load_lds_dwordx4 v[246:247], off
	s_mov_b64 s[98:99], s[84:85]
	s_waitcnt vmcnt(6) lgkmcnt(0)
	s_barrier
	s_cbranch_vccnz .LBB0_180
	s_waitcnt lgkmcnt(0)
	v_mfma_f32_16x16x32_bf16 v[54:57], v[146:149], v[174:177], v[54:57]
	v_mfma_f32_16x16x32_bf16 v[62:65], v[154:157], v[174:177], v[62:65]
	v_mfma_f32_16x16x32_bf16 v[38:41], v[146:149], v[170:173], v[38:41]
	v_mfma_f32_16x16x32_bf16 v[46:49], v[154:157], v[170:173], v[46:49]
	v_mfma_f32_16x16x32_bf16 v[22:25], v[146:149], v[166:169], v[22:25]
	v_mfma_f32_16x16x32_bf16 v[30:33], v[154:157], v[166:169], v[30:33]
	v_mfma_f32_16x16x32_bf16 v[10:13], v[146:149], v[162:165], v[10:13]
	v_mfma_f32_16x16x32_bf16 v[14:17], v[154:157], v[162:165], v[14:17]
	v_mfma_f32_16x16x32_bf16 v[54:57], v[150:153], v[190:193], v[54:57]
	v_mfma_f32_16x16x32_bf16 v[62:65], v[158:161], v[190:193], v[62:65]
	v_mfma_f32_16x16x32_bf16 v[38:41], v[150:153], v[186:189], v[38:41]
	v_mfma_f32_16x16x32_bf16 v[46:49], v[158:161], v[186:189], v[46:49]
	v_mfma_f32_16x16x32_bf16 v[22:25], v[150:153], v[182:185], v[22:25]
	v_mfma_f32_16x16x32_bf16 v[30:33], v[158:161], v[182:185], v[30:33]
	v_mfma_f32_16x16x32_bf16 v[10:13], v[150:153], v[178:181], v[10:13]
	v_mfma_f32_16x16x32_bf16 v[14:17], v[158:161], v[178:181], v[14:17]
	v_mfma_f32_16x16x32_bf16 v[58:61], v[130:133], v[174:177], v[58:61]
	v_mfma_f32_16x16x32_bf16 v[50:53], v[138:141], v[174:177], v[50:53]
	v_mfma_f32_16x16x32_bf16 v[42:45], v[130:133], v[170:173], v[42:45]
	v_mfma_f32_16x16x32_bf16 v[34:37], v[138:141], v[170:173], v[34:37]
	v_mfma_f32_16x16x32_bf16 v[26:29], v[130:133], v[166:169], v[26:29]
	v_mfma_f32_16x16x32_bf16 v[18:21], v[138:141], v[166:169], v[18:21]
	v_mfma_f32_16x16x32_bf16 v[6:9], v[130:133], v[162:165], v[6:9]
	v_mfma_f32_16x16x32_bf16 v[2:5], v[138:141], v[162:165], v[2:5]
	v_mfma_f32_16x16x32_bf16 v[58:61], v[134:137], v[190:193], v[58:61]
	v_mfma_f32_16x16x32_bf16 v[50:53], v[142:145], v[190:193], v[50:53]
	v_mfma_f32_16x16x32_bf16 v[42:45], v[134:137], v[186:189], v[42:45]
	v_mfma_f32_16x16x32_bf16 v[34:37], v[142:145], v[186:189], v[34:37]
	v_mfma_f32_16x16x32_bf16 v[26:29], v[134:137], v[182:185], v[26:29]
	v_mfma_f32_16x16x32_bf16 v[18:21], v[142:145], v[182:185], v[18:21]
	v_mfma_f32_16x16x32_bf16 v[6:9], v[134:137], v[178:181], v[6:9]
	v_mfma_f32_16x16x32_bf16 v[2:5], v[142:145], v[178:181], v[2:5]
.LBB0_180:
	s_and_b64 vcc, s[46:47], s[86:87]
	v_cndmask_b32_e64 v131, v233, 0, vcc
	v_cndmask_b32_e32 v130, v232, v198, vcc
	v_lshl_add_u64 v[246:247], s[84:85], 0, v[130:131]
	s_barrier
	s_mov_b32 m0, s8
	s_nop 0
	global_load_lds_dwordx4 v194, s[98:99]
	s_mov_b32 m0, s13
	s_nop 0
	global_load_lds_dwordx4 v196, s[98:99]
	v_add_u32_e32 v130, 0x18000, v243
	v_add_u32_e32 v142, 0x1c000, v243
	ds_read_b128 v[146:149], v130
	ds_read_b128 v[150:153], v130 offset:1024
	ds_read_b128 v[154:157], v130 offset:2048
	ds_read_b128 v[158:161], v130 offset:3072
	ds_read_b128 v[130:133], v142
	ds_read_b128 v[134:137], v142 offset:1024
	ds_read_b128 v[138:141], v142 offset:2048
	ds_read_b128 v[142:145], v142 offset:3072
	s_mov_b32 m0, s14
	v_lshl_add_u64 v[248:249], v[246:247], 0, v[194:195]
	s_waitcnt lgkmcnt(0)
	ds_read_b128 v[174:177], v244 offset:32768
	ds_read_b128 v[190:193], v244 offset:33792
	ds_read_b128 v[170:173], v244 offset:34816
	ds_read_b128 v[186:189], v244 offset:35840
	ds_read_b128 v[166:169], v244 offset:36864
	ds_read_b128 v[182:185], v244 offset:37888
	ds_read_b128 v[162:165], v244 offset:38912
	ds_read_b128 v[178:181], v244 offset:39936
	global_load_lds_dwordx4 v[248:249], off
	v_lshl_add_u64 v[246:247], v[246:247], 0, v[196:197]
	s_mov_b32 m0, s15
	s_nop 0
	global_load_lds_dwordx4 v[246:247], off
	s_waitcnt vmcnt(8) lgkmcnt(0)
	s_barrier
	v_mfma_f32_16x16x32_bf16 v[118:121], v[146:149], v[174:177], v[118:121]
	v_mfma_f32_16x16x32_bf16 v[126:129], v[154:157], v[174:177], v[126:129]
	v_mfma_f32_16x16x32_bf16 v[102:105], v[146:149], v[170:173], v[102:105]
	v_mfma_f32_16x16x32_bf16 v[110:113], v[154:157], v[170:173], v[110:113]
	v_mfma_f32_16x16x32_bf16 v[86:89], v[146:149], v[166:169], v[86:89]
	v_mfma_f32_16x16x32_bf16 v[94:97], v[154:157], v[166:169], v[94:97]
	v_mfma_f32_16x16x32_bf16 v[70:73], v[146:149], v[162:165], v[70:73]
	v_mfma_f32_16x16x32_bf16 v[78:81], v[154:157], v[162:165], v[78:81]
	v_mfma_f32_16x16x32_bf16 v[118:121], v[150:153], v[190:193], v[118:121]
	v_mfma_f32_16x16x32_bf16 v[126:129], v[158:161], v[190:193], v[126:129]
	v_mfma_f32_16x16x32_bf16 v[102:105], v[150:153], v[186:189], v[102:105]
	v_mfma_f32_16x16x32_bf16 v[110:113], v[158:161], v[186:189], v[110:113]
	v_mfma_f32_16x16x32_bf16 v[86:89], v[150:153], v[182:185], v[86:89]
	v_mfma_f32_16x16x32_bf16 v[94:97], v[158:161], v[182:185], v[94:97]
	v_mfma_f32_16x16x32_bf16 v[70:73], v[150:153], v[178:181], v[70:73]
	v_mfma_f32_16x16x32_bf16 v[78:81], v[158:161], v[178:181], v[78:81]
	v_mfma_f32_16x16x32_bf16 v[122:125], v[130:133], v[174:177], v[122:125]
	v_mfma_f32_16x16x32_bf16 v[114:117], v[138:141], v[174:177], v[114:117]
	v_mfma_f32_16x16x32_bf16 v[106:109], v[130:133], v[170:173], v[106:109]
	v_mfma_f32_16x16x32_bf16 v[98:101], v[138:141], v[170:173], v[98:101]
	v_mfma_f32_16x16x32_bf16 v[90:93], v[130:133], v[166:169], v[90:93]
	v_mfma_f32_16x16x32_bf16 v[82:85], v[138:141], v[166:169], v[82:85]
	v_mfma_f32_16x16x32_bf16 v[74:77], v[130:133], v[162:165], v[74:77]
	v_mfma_f32_16x16x32_bf16 v[66:69], v[138:141], v[162:165], v[66:69]
	v_mfma_f32_16x16x32_bf16 v[122:125], v[134:137], v[190:193], v[122:125]
	v_mfma_f32_16x16x32_bf16 v[114:117], v[142:145], v[190:193], v[114:117]
	v_mfma_f32_16x16x32_bf16 v[106:109], v[134:137], v[186:189], v[106:109]
	v_mfma_f32_16x16x32_bf16 v[98:101], v[142:145], v[186:189], v[98:101]
	v_mfma_f32_16x16x32_bf16 v[90:93], v[134:137], v[182:185], v[90:93]
	v_mfma_f32_16x16x32_bf16 v[82:85], v[142:145], v[182:185], v[82:85]
	v_mfma_f32_16x16x32_bf16 v[74:77], v[134:137], v[178:181], v[74:77]
	v_mfma_f32_16x16x32_bf16 v[66:69], v[142:145], v[178:181], v[66:69]
	s_barrier
	s_and_b64 vcc, exec, s[48:49]
	s_cbranch_vccnz .LBB0_182
	ds_read_b128 v[174:177], v244 offset:49152
	ds_read_b128 v[190:193], v244 offset:50176
	ds_read_b128 v[170:173], v244 offset:51200
	ds_read_b128 v[186:189], v244 offset:52224
	ds_read_b128 v[166:169], v244 offset:53248
	ds_read_b128 v[182:185], v244 offset:54272
	ds_read_b128 v[162:165], v244 offset:55296
	ds_read_b128 v[178:181], v244 offset:56320
.LBB0_182:
	s_add_u32 s86, s82, 0x120000
	s_addc_u32 s87, s83, 0
	s_add_u32 s84, s84, 0x230000
	s_addc_u32 s85, s85, 0
	s_mov_b32 m0, s17
	s_add_u32 s82, s82, 0x124000
	global_load_lds_dwordx4 v194, s[86:87]
	s_mov_b32 m0, s54
	s_addc_u32 s83, s83, 0
	global_load_lds_dwordx4 v196, s[86:87]
	s_mov_b32 m0, s89
	s_and_b64 vcc, exec, s[48:49]
	global_load_lds_dwordx4 v194, s[82:83]
	s_mov_b32 m0, s90
	s_nop 0
	global_load_lds_dwordx4 v196, s[82:83]
	s_mov_b64 s[100:101], s[84:85]
	s_waitcnt vmcnt(6) lgkmcnt(0)
	s_barrier
	s_cbranch_vccnz .LBB0_175
	s_waitcnt lgkmcnt(0)
	v_mfma_f32_16x16x32_bf16 v[54:57], v[146:149], v[174:177], v[54:57]
	v_mfma_f32_16x16x32_bf16 v[62:65], v[154:157], v[174:177], v[62:65]
	v_mfma_f32_16x16x32_bf16 v[38:41], v[146:149], v[170:173], v[38:41]
	v_mfma_f32_16x16x32_bf16 v[46:49], v[154:157], v[170:173], v[46:49]
	v_mfma_f32_16x16x32_bf16 v[22:25], v[146:149], v[166:169], v[22:25]
	v_mfma_f32_16x16x32_bf16 v[30:33], v[154:157], v[166:169], v[30:33]
	v_mfma_f32_16x16x32_bf16 v[10:13], v[146:149], v[162:165], v[10:13]
	v_mfma_f32_16x16x32_bf16 v[14:17], v[154:157], v[162:165], v[14:17]
	v_mfma_f32_16x16x32_bf16 v[54:57], v[150:153], v[190:193], v[54:57]
	v_mfma_f32_16x16x32_bf16 v[62:65], v[158:161], v[190:193], v[62:65]
	v_mfma_f32_16x16x32_bf16 v[38:41], v[150:153], v[186:189], v[38:41]
	v_mfma_f32_16x16x32_bf16 v[46:49], v[158:161], v[186:189], v[46:49]
	v_mfma_f32_16x16x32_bf16 v[22:25], v[150:153], v[182:185], v[22:25]
	v_mfma_f32_16x16x32_bf16 v[30:33], v[158:161], v[182:185], v[30:33]
	v_mfma_f32_16x16x32_bf16 v[10:13], v[150:153], v[178:181], v[10:13]
	v_mfma_f32_16x16x32_bf16 v[14:17], v[158:161], v[178:181], v[14:17]
	v_mfma_f32_16x16x32_bf16 v[58:61], v[130:133], v[174:177], v[58:61]
	v_mfma_f32_16x16x32_bf16 v[50:53], v[138:141], v[174:177], v[50:53]
	v_mfma_f32_16x16x32_bf16 v[42:45], v[130:133], v[170:173], v[42:45]
	v_mfma_f32_16x16x32_bf16 v[34:37], v[138:141], v[170:173], v[34:37]
	v_mfma_f32_16x16x32_bf16 v[26:29], v[130:133], v[166:169], v[26:29]
	v_mfma_f32_16x16x32_bf16 v[18:21], v[138:141], v[166:169], v[18:21]
	v_mfma_f32_16x16x32_bf16 v[6:9], v[130:133], v[162:165], v[6:9]
	v_mfma_f32_16x16x32_bf16 v[2:5], v[138:141], v[162:165], v[2:5]
	v_mfma_f32_16x16x32_bf16 v[58:61], v[134:137], v[190:193], v[58:61]
	v_mfma_f32_16x16x32_bf16 v[50:53], v[142:145], v[190:193], v[50:53]
	v_mfma_f32_16x16x32_bf16 v[42:45], v[134:137], v[186:189], v[42:45]
	v_mfma_f32_16x16x32_bf16 v[34:37], v[142:145], v[186:189], v[34:37]
	v_mfma_f32_16x16x32_bf16 v[26:29], v[134:137], v[182:185], v[26:29]
	v_mfma_f32_16x16x32_bf16 v[18:21], v[142:145], v[182:185], v[18:21]
	v_mfma_f32_16x16x32_bf16 v[6:9], v[134:137], v[178:181], v[6:9]
	v_mfma_f32_16x16x32_bf16 v[2:5], v[142:145], v[178:181], v[2:5]
	s_branch .LBB0_175

.LBB0_559:
	s_mov_b32 m0, s55
	s_nop 0
	global_load_lds_dwordx4 v194, s[100:101]
	s_mov_b32 m0, s67
	s_nop 0
	global_load_lds_dwordx4 v196, s[100:101]
	ds_read_b128 v[146:149], v227
	ds_read_b128 v[150:153], v227 offset:1024
	ds_read_b128 v[154:157], v227 offset:2048
	ds_read_b128 v[158:161], v227 offset:3072
	ds_read_b128 v[130:133], v228
	ds_read_b128 v[134:137], v228 offset:1024
	ds_read_b128 v[138:141], v228 offset:2048
	ds_read_b128 v[142:145], v228 offset:3072
	v_lshl_add_u64 v[234:235], v[216:217], 0, s[58:59]
	s_add_i32 m0, s8, 0xc000
	s_waitcnt lgkmcnt(0)
	ds_read_b128 v[174:177], v229
	ds_read_b128 v[190:193], v229 offset:1024
	ds_read_b128 v[170:173], v229 offset:2048
	ds_read_b128 v[186:189], v229 offset:3072
	ds_read_b128 v[166:169], v229 offset:4096
	ds_read_b128 v[182:185], v229 offset:5120
	ds_read_b128 v[162:165], v229 offset:6144
	ds_read_b128 v[178:181], v229 offset:7168
	global_load_lds_dwordx4 v[234:235], off
	v_lshl_add_u64 v[234:235], v[218:219], 0, s[58:59]
	s_add_i32 m0, s8, 0xe000
	s_nop 0
	global_load_lds_dwordx4 v[234:235], off
	s_waitcnt vmcnt(8) lgkmcnt(0)
	s_barrier
	v_mfma_f32_16x16x32_bf16 v[126:129], v[146:149], v[174:177], v[126:129]
	v_mfma_f32_16x16x32_bf16 v[122:125], v[154:157], v[174:177], v[122:125]
	v_mfma_f32_16x16x32_bf16 v[110:113], v[146:149], v[170:173], v[110:113]
	v_mfma_f32_16x16x32_bf16 v[106:109], v[154:157], v[170:173], v[106:109]
	v_mfma_f32_16x16x32_bf16 v[94:97], v[146:149], v[166:169], v[94:97]
	v_mfma_f32_16x16x32_bf16 v[90:93], v[154:157], v[166:169], v[90:93]
	v_mfma_f32_16x16x32_bf16 v[78:81], v[146:149], v[162:165], v[78:81]
	v_mfma_f32_16x16x32_bf16 v[74:77], v[154:157], v[162:165], v[74:77]
	v_mfma_f32_16x16x32_bf16 v[126:129], v[150:153], v[190:193], v[126:129]
	v_mfma_f32_16x16x32_bf16 v[122:125], v[158:161], v[190:193], v[122:125]
	v_mfma_f32_16x16x32_bf16 v[110:113], v[150:153], v[186:189], v[110:113]
	v_mfma_f32_16x16x32_bf16 v[106:109], v[158:161], v[186:189], v[106:109]
	v_mfma_f32_16x16x32_bf16 v[94:97], v[150:153], v[182:185], v[94:97]
	v_mfma_f32_16x16x32_bf16 v[90:93], v[158:161], v[182:185], v[90:93]
	v_mfma_f32_16x16x32_bf16 v[78:81], v[150:153], v[178:181], v[78:81]
	v_mfma_f32_16x16x32_bf16 v[74:77], v[158:161], v[178:181], v[74:77]
	v_mfma_f32_16x16x32_bf16 v[118:121], v[130:133], v[174:177], v[118:121]
	v_mfma_f32_16x16x32_bf16 v[114:117], v[138:141], v[174:177], v[114:117]
	v_mfma_f32_16x16x32_bf16 v[102:105], v[130:133], v[170:173], v[102:105]
	v_mfma_f32_16x16x32_bf16 v[98:101], v[138:141], v[170:173], v[98:101]
	v_mfma_f32_16x16x32_bf16 v[86:89], v[130:133], v[166:169], v[86:89]
	v_mfma_f32_16x16x32_bf16 v[82:85], v[138:141], v[166:169], v[82:85]
	v_mfma_f32_16x16x32_bf16 v[70:73], v[130:133], v[162:165], v[70:73]
	v_mfma_f32_16x16x32_bf16 v[66:69], v[138:141], v[162:165], v[66:69]
	v_mfma_f32_16x16x32_bf16 v[118:121], v[134:137], v[190:193], v[118:121]
	v_mfma_f32_16x16x32_bf16 v[114:117], v[142:145], v[190:193], v[114:117]
	v_mfma_f32_16x16x32_bf16 v[102:105], v[134:137], v[186:189], v[102:105]
	v_mfma_f32_16x16x32_bf16 v[98:101], v[142:145], v[186:189], v[98:101]
	v_mfma_f32_16x16x32_bf16 v[86:89], v[134:137], v[182:185], v[86:89]
	v_mfma_f32_16x16x32_bf16 v[82:85], v[142:145], v[182:185], v[82:85]
	v_mfma_f32_16x16x32_bf16 v[70:73], v[134:137], v[178:181], v[70:73]
	v_mfma_f32_16x16x32_bf16 v[66:69], v[142:145], v[178:181], v[66:69]
	s_barrier
	v_cmp_ne_u32_e64 s[42:43], 1, v233
	s_andn2_b64 vcc, exec, s[44:45]
	s_cbranch_vccnz .LBB0_561
	ds_read_b128 v[174:177], v229 offset:16384
	ds_read_b128 v[190:193], v229 offset:17408
	ds_read_b128 v[170:173], v229 offset:18432
	ds_read_b128 v[186:189], v229 offset:19456
	ds_read_b128 v[166:169], v229 offset:20480
	ds_read_b128 v[182:185], v229 offset:21504
	ds_read_b128 v[162:165], v229 offset:22528
	ds_read_b128 v[178:181], v229 offset:23552
.LBB0_561:
	s_add_u32 s60, s56, s58
	s_addc_u32 s61, s57, s59
	s_add_u32 s62, s60, 0x440000
	s_addc_u32 s63, s61, 0
	s_cmp_eq_u32 s58, 0x3fc0000
	s_cselect_b64 s[68:69], -1, 0
	s_and_b64 s[60:61], s[68:69], exec
	s_cselect_b32 s61, s37, s72
	s_cselect_b32 s60, s47, s53
	s_mov_b32 m0, s9
	s_cselect_b32 s63, s1, s63
	s_cselect_b32 s62, s24, s62
	s_add_u32 s74, s60, 0x4000
	global_load_lds_dwordx4 v194, s[60:61]
	s_mov_b32 m0, s10
	s_addc_u32 s75, s61, 0
	global_load_lds_dwordx4 v196, s[60:61]
	s_mov_b32 m0, s11
	s_and_b64 vcc, exec, s[42:43]
	global_load_lds_dwordx4 v194, s[74:75]
	s_mov_b32 m0, s12
	s_nop 0
	global_load_lds_dwordx4 v196, s[74:75]
	s_mov_b64 s[98:99], s[62:63]
	s_waitcnt vmcnt(6) lgkmcnt(0)
	s_barrier
	s_cbranch_vccnz .LBB0_563
	s_waitcnt lgkmcnt(0)
	v_mfma_f32_16x16x32_bf16 v[62:65], v[146:149], v[174:177], v[62:65]
	v_mfma_f32_16x16x32_bf16 v[58:61], v[154:157], v[174:177], v[58:61]
	v_mfma_f32_16x16x32_bf16 v[46:49], v[146:149], v[170:173], v[46:49]
	v_mfma_f32_16x16x32_bf16 v[42:45], v[154:157], v[170:173], v[42:45]
	v_mfma_f32_16x16x32_bf16 v[30:33], v[146:149], v[166:169], v[30:33]
	v_mfma_f32_16x16x32_bf16 v[26:29], v[154:157], v[166:169], v[26:29]
	v_mfma_f32_16x16x32_bf16 v[14:17], v[146:149], v[162:165], v[14:17]
	v_mfma_f32_16x16x32_bf16 v[10:13], v[154:157], v[162:165], v[10:13]
	v_mfma_f32_16x16x32_bf16 v[62:65], v[150:153], v[190:193], v[62:65]
	v_mfma_f32_16x16x32_bf16 v[58:61], v[158:161], v[190:193], v[58:61]
	v_mfma_f32_16x16x32_bf16 v[46:49], v[150:153], v[186:189], v[46:49]
	v_mfma_f32_16x16x32_bf16 v[42:45], v[158:161], v[186:189], v[42:45]
	v_mfma_f32_16x16x32_bf16 v[30:33], v[150:153], v[182:185], v[30:33]
	v_mfma_f32_16x16x32_bf16 v[26:29], v[158:161], v[182:185], v[26:29]
	v_mfma_f32_16x16x32_bf16 v[14:17], v[150:153], v[178:181], v[14:17]
	v_mfma_f32_16x16x32_bf16 v[10:13], v[158:161], v[178:181], v[10:13]
	v_mfma_f32_16x16x32_bf16 v[54:57], v[130:133], v[174:177], v[54:57]
	v_mfma_f32_16x16x32_bf16 v[50:53], v[138:141], v[174:177], v[50:53]
	v_mfma_f32_16x16x32_bf16 v[38:41], v[130:133], v[170:173], v[38:41]
	v_mfma_f32_16x16x32_bf16 v[34:37], v[138:141], v[170:173], v[34:37]
	v_mfma_f32_16x16x32_bf16 v[22:25], v[130:133], v[166:169], v[22:25]
	v_mfma_f32_16x16x32_bf16 v[18:21], v[138:141], v[166:169], v[18:21]
	v_mfma_f32_16x16x32_bf16 v[6:9], v[130:133], v[162:165], v[6:9]
	v_mfma_f32_16x16x32_bf16 v[2:5], v[138:141], v[162:165], v[2:5]
	v_mfma_f32_16x16x32_bf16 v[54:57], v[134:137], v[190:193], v[54:57]
	v_mfma_f32_16x16x32_bf16 v[50:53], v[142:145], v[190:193], v[50:53]
	v_mfma_f32_16x16x32_bf16 v[38:41], v[134:137], v[186:189], v[38:41]
	v_mfma_f32_16x16x32_bf16 v[34:37], v[142:145], v[186:189], v[34:37]
	v_mfma_f32_16x16x32_bf16 v[22:25], v[134:137], v[182:185], v[22:25]
	v_mfma_f32_16x16x32_bf16 v[18:21], v[142:145], v[182:185], v[18:21]
	v_mfma_f32_16x16x32_bf16 v[6:9], v[134:137], v[178:181], v[6:9]
	v_mfma_f32_16x16x32_bf16 v[2:5], v[142:145], v[178:181], v[2:5]
.LBB0_563:
	s_and_b64 vcc, s[40:41], s[68:69]
	v_cndmask_b32_e64 v131, v215, 0, vcc
	v_cndmask_b32_e32 v130, v214, v198, vcc
	v_lshl_add_u64 v[234:235], s[62:63], 0, v[130:131]
	s_barrier
	s_mov_b32 m0, s8
	s_nop 0
	global_load_lds_dwordx4 v194, s[98:99]
	s_mov_b32 m0, s13
	s_nop 0
	global_load_lds_dwordx4 v196, s[98:99]
	v_add_u32_e32 v130, 0x18000, v226
	v_add_u32_e32 v142, 0x1c000, v226
	ds_read_b128 v[146:149], v130
	ds_read_b128 v[150:153], v130 offset:1024
	ds_read_b128 v[154:157], v130 offset:2048
	ds_read_b128 v[158:161], v130 offset:3072
	ds_read_b128 v[130:133], v142
	ds_read_b128 v[134:137], v142 offset:1024
	ds_read_b128 v[138:141], v142 offset:2048
	ds_read_b128 v[142:145], v142 offset:3072
	s_mov_b32 m0, s14
	v_lshl_add_u64 v[236:237], v[234:235], 0, v[194:195]
	s_waitcnt lgkmcnt(0)
	ds_read_b128 v[174:177], v229 offset:32768
	ds_read_b128 v[190:193], v229 offset:33792
	ds_read_b128 v[170:173], v229 offset:34816
	ds_read_b128 v[186:189], v229 offset:35840
	ds_read_b128 v[166:169], v229 offset:36864
	ds_read_b128 v[182:185], v229 offset:37888
	ds_read_b128 v[162:165], v229 offset:38912
	ds_read_b128 v[178:181], v229 offset:39936
	global_load_lds_dwordx4 v[236:237], off
	v_lshl_add_u64 v[234:235], v[234:235], 0, v[196:197]
	s_mov_b32 m0, s15
	s_nop 0
	global_load_lds_dwordx4 v[234:235], off
	s_waitcnt vmcnt(8) lgkmcnt(0)
	s_barrier
	v_mfma_f32_16x16x32_bf16 v[126:129], v[146:149], v[174:177], v[126:129]
	v_mfma_f32_16x16x32_bf16 v[122:125], v[154:157], v[174:177], v[122:125]
	v_mfma_f32_16x16x32_bf16 v[110:113], v[146:149], v[170:173], v[110:113]
	v_mfma_f32_16x16x32_bf16 v[106:109], v[154:157], v[170:173], v[106:109]
	v_mfma_f32_16x16x32_bf16 v[94:97], v[146:149], v[166:169], v[94:97]
	v_mfma_f32_16x16x32_bf16 v[90:93], v[154:157], v[166:169], v[90:93]
	v_mfma_f32_16x16x32_bf16 v[78:81], v[146:149], v[162:165], v[78:81]
	v_mfma_f32_16x16x32_bf16 v[74:77], v[154:157], v[162:165], v[74:77]
	v_mfma_f32_16x16x32_bf16 v[126:129], v[150:153], v[190:193], v[126:129]
	v_mfma_f32_16x16x32_bf16 v[122:125], v[158:161], v[190:193], v[122:125]
	v_mfma_f32_16x16x32_bf16 v[110:113], v[150:153], v[186:189], v[110:113]
	v_mfma_f32_16x16x32_bf16 v[106:109], v[158:161], v[186:189], v[106:109]
	v_mfma_f32_16x16x32_bf16 v[94:97], v[150:153], v[182:185], v[94:97]
	v_mfma_f32_16x16x32_bf16 v[90:93], v[158:161], v[182:185], v[90:93]
	v_mfma_f32_16x16x32_bf16 v[78:81], v[150:153], v[178:181], v[78:81]
	v_mfma_f32_16x16x32_bf16 v[74:77], v[158:161], v[178:181], v[74:77]
	v_mfma_f32_16x16x32_bf16 v[118:121], v[130:133], v[174:177], v[118:121]
	v_mfma_f32_16x16x32_bf16 v[114:117], v[138:141], v[174:177], v[114:117]
	v_mfma_f32_16x16x32_bf16 v[102:105], v[130:133], v[170:173], v[102:105]
	v_mfma_f32_16x16x32_bf16 v[98:101], v[138:141], v[170:173], v[98:101]
	v_mfma_f32_16x16x32_bf16 v[86:89], v[130:133], v[166:169], v[86:89]
	v_mfma_f32_16x16x32_bf16 v[82:85], v[138:141], v[166:169], v[82:85]
	v_mfma_f32_16x16x32_bf16 v[70:73], v[130:133], v[162:165], v[70:73]
	v_mfma_f32_16x16x32_bf16 v[66:69], v[138:141], v[162:165], v[66:69]
	v_mfma_f32_16x16x32_bf16 v[118:121], v[134:137], v[190:193], v[118:121]
	v_mfma_f32_16x16x32_bf16 v[114:117], v[142:145], v[190:193], v[114:117]
	v_mfma_f32_16x16x32_bf16 v[102:105], v[134:137], v[186:189], v[102:105]
	v_mfma_f32_16x16x32_bf16 v[98:101], v[142:145], v[186:189], v[98:101]
	v_mfma_f32_16x16x32_bf16 v[86:89], v[134:137], v[182:185], v[86:89]
	v_mfma_f32_16x16x32_bf16 v[82:85], v[142:145], v[182:185], v[82:85]
	v_mfma_f32_16x16x32_bf16 v[70:73], v[134:137], v[178:181], v[70:73]
	v_mfma_f32_16x16x32_bf16 v[66:69], v[142:145], v[178:181], v[66:69]
	s_barrier
	s_and_b64 vcc, exec, s[42:43]
	s_cbranch_vccnz .LBB0_565
	ds_read_b128 v[174:177], v229 offset:49152
	ds_read_b128 v[190:193], v229 offset:50176
	ds_read_b128 v[170:173], v229 offset:51200
	ds_read_b128 v[186:189], v229 offset:52224
	ds_read_b128 v[166:169], v229 offset:53248
	ds_read_b128 v[182:185], v229 offset:54272
	ds_read_b128 v[162:165], v229 offset:55296
	ds_read_b128 v[178:181], v229 offset:56320
.LBB0_565:
	s_add_u32 s68, s60, 0x40000
	s_addc_u32 s69, s61, 0
	s_add_u32 s62, s62, 0x220000
	s_addc_u32 s63, s63, 0
	s_mov_b32 m0, s17
	s_add_u32 s60, s60, 0x44000
	global_load_lds_dwordx4 v194, s[68:69]
	s_mov_b32 m0, s54
	s_addc_u32 s61, s61, 0
	global_load_lds_dwordx4 v196, s[68:69]
	s_mov_b32 m0, s70
	s_and_b64 vcc, exec, s[42:43]
	global_load_lds_dwordx4 v194, s[60:61]
	s_mov_b32 m0, s71
	s_nop 0
	global_load_lds_dwordx4 v196, s[60:61]
	s_mov_b64 s[100:101], s[62:63]
	s_waitcnt vmcnt(6) lgkmcnt(0)
	s_barrier
	s_cbranch_vccnz .LBB0_558
	s_waitcnt lgkmcnt(0)
	v_mfma_f32_16x16x32_bf16 v[62:65], v[146:149], v[174:177], v[62:65]
	v_mfma_f32_16x16x32_bf16 v[58:61], v[154:157], v[174:177], v[58:61]
	v_mfma_f32_16x16x32_bf16 v[46:49], v[146:149], v[170:173], v[46:49]
	v_mfma_f32_16x16x32_bf16 v[42:45], v[154:157], v[170:173], v[42:45]
	v_mfma_f32_16x16x32_bf16 v[30:33], v[146:149], v[166:169], v[30:33]
	v_mfma_f32_16x16x32_bf16 v[26:29], v[154:157], v[166:169], v[26:29]
	v_mfma_f32_16x16x32_bf16 v[14:17], v[146:149], v[162:165], v[14:17]
	v_mfma_f32_16x16x32_bf16 v[10:13], v[154:157], v[162:165], v[10:13]
	v_mfma_f32_16x16x32_bf16 v[62:65], v[150:153], v[190:193], v[62:65]
	v_mfma_f32_16x16x32_bf16 v[58:61], v[158:161], v[190:193], v[58:61]
	v_mfma_f32_16x16x32_bf16 v[46:49], v[150:153], v[186:189], v[46:49]
	v_mfma_f32_16x16x32_bf16 v[42:45], v[158:161], v[186:189], v[42:45]
	v_mfma_f32_16x16x32_bf16 v[30:33], v[150:153], v[182:185], v[30:33]
	v_mfma_f32_16x16x32_bf16 v[26:29], v[158:161], v[182:185], v[26:29]
	v_mfma_f32_16x16x32_bf16 v[14:17], v[150:153], v[178:181], v[14:17]
	v_mfma_f32_16x16x32_bf16 v[10:13], v[158:161], v[178:181], v[10:13]
	v_mfma_f32_16x16x32_bf16 v[54:57], v[130:133], v[174:177], v[54:57]
	v_mfma_f32_16x16x32_bf16 v[50:53], v[138:141], v[174:177], v[50:53]
	v_mfma_f32_16x16x32_bf16 v[38:41], v[130:133], v[170:173], v[38:41]
	v_mfma_f32_16x16x32_bf16 v[34:37], v[138:141], v[170:173], v[34:37]
	v_mfma_f32_16x16x32_bf16 v[22:25], v[130:133], v[166:169], v[22:25]
	v_mfma_f32_16x16x32_bf16 v[18:21], v[138:141], v[166:169], v[18:21]
	v_mfma_f32_16x16x32_bf16 v[6:9], v[130:133], v[162:165], v[6:9]
	v_mfma_f32_16x16x32_bf16 v[2:5], v[138:141], v[162:165], v[2:5]
	v_mfma_f32_16x16x32_bf16 v[54:57], v[134:137], v[190:193], v[54:57]
	v_mfma_f32_16x16x32_bf16 v[50:53], v[142:145], v[190:193], v[50:53]
	v_mfma_f32_16x16x32_bf16 v[38:41], v[134:137], v[186:189], v[38:41]
	v_mfma_f32_16x16x32_bf16 v[34:37], v[142:145], v[186:189], v[34:37]
	v_mfma_f32_16x16x32_bf16 v[22:25], v[134:137], v[182:185], v[22:25]
	v_mfma_f32_16x16x32_bf16 v[18:21], v[142:145], v[182:185], v[18:21]
	v_mfma_f32_16x16x32_bf16 v[6:9], v[134:137], v[178:181], v[6:9]
	v_mfma_f32_16x16x32_bf16 v[2:5], v[142:145], v[178:181], v[2:5]
	s_branch .LBB0_558

.LBB0_761:
	s_mov_b32 m0, s14
	s_nop 0
	global_load_lds_dwordx4 v194, s[100:101]
	s_mov_b32 m0, s15
	s_nop 0
	global_load_lds_dwordx4 v196, s[100:101]
	ds_read_b128 v[130:133], v237
	ds_read_b128 v[134:137], v237 offset:1024
	ds_read_b128 v[138:141], v237 offset:2048
	ds_read_b128 v[142:145], v237 offset:3072
	ds_read_b128 v[146:149], v238
	ds_read_b128 v[150:153], v238 offset:1024
	ds_read_b128 v[154:157], v238 offset:2048
	ds_read_b128 v[158:161], v238 offset:3072
	s_add_u32 s48, s0, 0x21c000
	s_addc_u32 s49, s1, 0
	s_cmp_eq_u32 s67, 28
	s_cselect_b32 s42, s55, s62
	s_cselect_b32 s43, s29, s63
	s_cselect_b32 s52, s45, s48
	s_cselect_b32 s53, s31, s49
	s_add_u32 s50, s42, 0xe0000
	s_addc_u32 s51, s43, 0
	s_add_u32 s48, s52, 0x220000
	s_addc_u32 s49, s53, 0
	v_lshl_add_u64 v[208:209], s[0:1], 0, v[202:203]
	s_add_i32 m0, s9, 0xc000
	ds_read_b128 v[162:165], v239
	ds_read_b128 v[166:169], v239 offset:1024
	ds_read_b128 v[170:173], v239 offset:2048
	ds_read_b128 v[174:177], v239 offset:3072
	ds_read_b128 v[178:181], v239 offset:4096
	ds_read_b128 v[182:185], v239 offset:5120
	ds_read_b128 v[186:189], v239 offset:6144
	ds_read_b128 v[190:193], v239 offset:7168
	global_load_lds_dwordx4 v[208:209], off
	v_lshl_add_u64 v[208:209], s[0:1], 0, v[200:201]
	s_add_i32 m0, s9, 0xe000
	s_nop 0
	global_load_lds_dwordx4 v[208:209], off
	s_waitcnt vmcnt(8) lgkmcnt(0)
	s_barrier
	v_mfma_f32_16x16x32_bf16 v[126:129], v[130:133], v[162:165], v[126:129]
	v_mfma_f32_16x16x32_bf16 v[122:125], v[138:141], v[162:165], v[122:125]
	v_mfma_f32_16x16x32_bf16 v[118:121], v[130:133], v[170:173], v[118:121]
	v_mfma_f32_16x16x32_bf16 v[114:117], v[138:141], v[170:173], v[114:117]
	v_mfma_f32_16x16x32_bf16 v[110:113], v[130:133], v[178:181], v[110:113]
	v_mfma_f32_16x16x32_bf16 v[106:109], v[138:141], v[178:181], v[106:109]
	v_mfma_f32_16x16x32_bf16 v[102:105], v[130:133], v[186:189], v[102:105]
	v_mfma_f32_16x16x32_bf16 v[98:101], v[138:141], v[186:189], v[98:101]
	v_mfma_f32_16x16x32_bf16 v[126:129], v[134:137], v[166:169], v[126:129]
	v_mfma_f32_16x16x32_bf16 v[122:125], v[142:145], v[166:169], v[122:125]
	v_mfma_f32_16x16x32_bf16 v[118:121], v[134:137], v[174:177], v[118:121]
	v_mfma_f32_16x16x32_bf16 v[114:117], v[142:145], v[174:177], v[114:117]
	v_mfma_f32_16x16x32_bf16 v[110:113], v[134:137], v[182:185], v[110:113]
	v_mfma_f32_16x16x32_bf16 v[106:109], v[142:145], v[182:185], v[106:109]
	v_mfma_f32_16x16x32_bf16 v[102:105], v[134:137], v[190:193], v[102:105]
	v_mfma_f32_16x16x32_bf16 v[98:101], v[142:145], v[190:193], v[98:101]
	v_mfma_f32_16x16x32_bf16 v[62:65], v[146:149], v[162:165], v[62:65]
	s_add_u32 s60, s52, 0x4000
	s_addc_u32 s61, s53, 0
	v_mfma_f32_16x16x32_bf16 v[58:61], v[154:157], v[162:165], v[58:61]
	v_mfma_f32_16x16x32_bf16 v[54:57], v[146:149], v[170:173], v[54:57]
	v_mfma_f32_16x16x32_bf16 v[50:53], v[154:157], v[170:173], v[50:53]
	v_mfma_f32_16x16x32_bf16 v[46:49], v[146:149], v[178:181], v[46:49]
	v_mfma_f32_16x16x32_bf16 v[42:45], v[154:157], v[178:181], v[42:45]
	v_mfma_f32_16x16x32_bf16 v[38:41], v[146:149], v[186:189], v[38:41]
	v_mfma_f32_16x16x32_bf16 v[34:37], v[154:157], v[186:189], v[34:37]
	v_mfma_f32_16x16x32_bf16 v[62:65], v[150:153], v[166:169], v[62:65]
	v_mfma_f32_16x16x32_bf16 v[58:61], v[158:161], v[166:169], v[58:61]
	v_mfma_f32_16x16x32_bf16 v[54:57], v[150:153], v[174:177], v[54:57]
	v_mfma_f32_16x16x32_bf16 v[50:53], v[158:161], v[174:177], v[50:53]
	v_mfma_f32_16x16x32_bf16 v[46:49], v[150:153], v[182:185], v[46:49]
	v_mfma_f32_16x16x32_bf16 v[42:45], v[158:161], v[182:185], v[42:45]
	v_mfma_f32_16x16x32_bf16 v[38:41], v[150:153], v[190:193], v[38:41]
	v_mfma_f32_16x16x32_bf16 v[34:37], v[158:161], v[190:193], v[34:37]
	s_barrier
	s_add_i32 s68, s16, s8
	s_mov_b32 m0, s68
	ds_read_b128 v[162:165], v239 offset:16384
	ds_read_b128 v[166:169], v239 offset:17408
	ds_read_b128 v[170:173], v239 offset:18432
	ds_read_b128 v[174:177], v239 offset:19456
	ds_read_b128 v[178:181], v239 offset:20480
	ds_read_b128 v[182:185], v239 offset:21504
	ds_read_b128 v[186:189], v239 offset:22528
	ds_read_b128 v[190:193], v239 offset:23552
	global_load_lds_dwordx4 v194, s[42:43]
	s_add_i32 m0, s68, 0x2000
	s_add_u32 s68, s42, 0x4000
	s_addc_u32 s69, s43, 0
	s_add_i32 s70, s17, s8
	global_load_lds_dwordx4 v196, s[42:43]
	s_mov_b32 m0, s70
	s_nop 0
	global_load_lds_dwordx4 v194, s[68:69]
	s_add_i32 m0, s70, 0x2000
	s_nop 0
	global_load_lds_dwordx4 v196, s[68:69]
	s_mov_b64 s[98:99], s[52:53]
	s_waitcnt vmcnt(6) lgkmcnt(0)
	s_barrier
	v_mfma_f32_16x16x32_bf16 v[94:97], v[130:133], v[162:165], v[94:97]
	v_mfma_f32_16x16x32_bf16 v[90:93], v[138:141], v[162:165], v[90:93]
	v_mfma_f32_16x16x32_bf16 v[86:89], v[130:133], v[170:173], v[86:89]
	v_mfma_f32_16x16x32_bf16 v[82:85], v[138:141], v[170:173], v[82:85]
	v_mfma_f32_16x16x32_bf16 v[78:81], v[130:133], v[178:181], v[78:81]
	v_mfma_f32_16x16x32_bf16 v[74:77], v[138:141], v[178:181], v[74:77]
	v_mfma_f32_16x16x32_bf16 v[70:73], v[130:133], v[186:189], v[70:73]
	v_mfma_f32_16x16x32_bf16 v[66:69], v[138:141], v[186:189], v[66:69]
	v_mfma_f32_16x16x32_bf16 v[94:97], v[134:137], v[166:169], v[94:97]
	v_mfma_f32_16x16x32_bf16 v[90:93], v[142:145], v[166:169], v[90:93]
	v_mfma_f32_16x16x32_bf16 v[86:89], v[134:137], v[174:177], v[86:89]
	v_mfma_f32_16x16x32_bf16 v[82:85], v[142:145], v[174:177], v[82:85]
	v_mfma_f32_16x16x32_bf16 v[78:81], v[134:137], v[182:185], v[78:81]
	v_mfma_f32_16x16x32_bf16 v[74:77], v[142:145], v[182:185], v[74:77]
	v_mfma_f32_16x16x32_bf16 v[70:73], v[134:137], v[190:193], v[70:73]
	v_mfma_f32_16x16x32_bf16 v[66:69], v[142:145], v[190:193], v[66:69]
	v_mfma_f32_16x16x32_bf16 v[30:33], v[146:149], v[162:165], v[30:33]
	v_mfma_f32_16x16x32_bf16 v[26:29], v[154:157], v[162:165], v[26:29]
	v_mfma_f32_16x16x32_bf16 v[22:25], v[146:149], v[170:173], v[22:25]
	v_mfma_f32_16x16x32_bf16 v[18:21], v[154:157], v[170:173], v[18:21]
	v_mfma_f32_16x16x32_bf16 v[14:17], v[146:149], v[178:181], v[14:17]
	v_mfma_f32_16x16x32_bf16 v[10:13], v[154:157], v[178:181], v[10:13]
	v_mfma_f32_16x16x32_bf16 v[6:9], v[146:149], v[186:189], v[6:9]
	v_mfma_f32_16x16x32_bf16 v[2:5], v[154:157], v[186:189], v[2:5]
	v_mfma_f32_16x16x32_bf16 v[30:33], v[150:153], v[166:169], v[30:33]
	v_mfma_f32_16x16x32_bf16 v[26:29], v[158:161], v[166:169], v[26:29]
	v_mfma_f32_16x16x32_bf16 v[22:25], v[150:153], v[174:177], v[22:25]
	v_mfma_f32_16x16x32_bf16 v[18:21], v[158:161], v[174:177], v[18:21]
	v_mfma_f32_16x16x32_bf16 v[14:17], v[150:153], v[182:185], v[14:17]
	v_mfma_f32_16x16x32_bf16 v[10:13], v[158:161], v[182:185], v[10:13]
	v_mfma_f32_16x16x32_bf16 v[6:9], v[150:153], v[190:193], v[6:9]
	v_mfma_f32_16x16x32_bf16 v[2:5], v[158:161], v[190:193], v[2:5]
	s_barrier
	s_mov_b32 m0, s9
	s_nop 0
	global_load_lds_dwordx4 v194, s[98:99]
	s_mov_b32 m0, s10
	s_nop 0
	global_load_lds_dwordx4 v196, s[98:99]
	s_add_i32 s52, 0, 0x18000
	s_add_i32 s53, 0, 0x1c000
	v_add_u32_e32 v142, s52, v228
	v_add_u32_e32 v158, s53, v228
	ds_read_b128 v[130:133], v142
	ds_read_b128 v[134:137], v142 offset:1024
	ds_read_b128 v[138:141], v142 offset:2048
	ds_read_b128 v[142:145], v142 offset:3072
	ds_read_b128 v[146:149], v158
	ds_read_b128 v[150:153], v158 offset:1024
	ds_read_b128 v[154:157], v158 offset:2048
	ds_read_b128 v[158:161], v158 offset:3072
	s_mov_b32 m0, s11
	ds_read_b128 v[162:165], v239 offset:32768
	ds_read_b128 v[166:169], v239 offset:33792
	ds_read_b128 v[170:173], v239 offset:34816
	ds_read_b128 v[174:177], v239 offset:35840
	ds_read_b128 v[178:181], v239 offset:36864
	ds_read_b128 v[182:185], v239 offset:37888
	ds_read_b128 v[186:189], v239 offset:38912
	ds_read_b128 v[190:193], v239 offset:39936
	global_load_lds_dwordx4 v194, s[60:61]
	s_mov_b32 m0, s12
	s_nop 0
	global_load_lds_dwordx4 v196, s[60:61]
	s_waitcnt vmcnt(8) lgkmcnt(0)
	s_barrier
	v_mfma_f32_16x16x32_bf16 v[126:129], v[130:133], v[162:165], v[126:129]
	v_mfma_f32_16x16x32_bf16 v[122:125], v[138:141], v[162:165], v[122:125]
	v_mfma_f32_16x16x32_bf16 v[118:121], v[130:133], v[170:173], v[118:121]
	v_mfma_f32_16x16x32_bf16 v[114:117], v[138:141], v[170:173], v[114:117]
	v_mfma_f32_16x16x32_bf16 v[110:113], v[130:133], v[178:181], v[110:113]
	v_mfma_f32_16x16x32_bf16 v[106:109], v[138:141], v[178:181], v[106:109]
	v_mfma_f32_16x16x32_bf16 v[102:105], v[130:133], v[186:189], v[102:105]
	v_mfma_f32_16x16x32_bf16 v[98:101], v[138:141], v[186:189], v[98:101]
	v_mfma_f32_16x16x32_bf16 v[126:129], v[134:137], v[166:169], v[126:129]
	v_mfma_f32_16x16x32_bf16 v[122:125], v[142:145], v[166:169], v[122:125]
	v_mfma_f32_16x16x32_bf16 v[118:121], v[134:137], v[174:177], v[118:121]
	v_mfma_f32_16x16x32_bf16 v[114:117], v[142:145], v[174:177], v[114:117]
	v_mfma_f32_16x16x32_bf16 v[110:113], v[134:137], v[182:185], v[110:113]
	v_mfma_f32_16x16x32_bf16 v[106:109], v[142:145], v[182:185], v[106:109]
	v_mfma_f32_16x16x32_bf16 v[102:105], v[134:137], v[190:193], v[102:105]
	v_mfma_f32_16x16x32_bf16 v[98:101], v[142:145], v[190:193], v[98:101]
	v_mfma_f32_16x16x32_bf16 v[62:65], v[146:149], v[162:165], v[62:65]
	v_mfma_f32_16x16x32_bf16 v[58:61], v[154:157], v[162:165], v[58:61]
	v_mfma_f32_16x16x32_bf16 v[54:57], v[146:149], v[170:173], v[54:57]
	v_mfma_f32_16x16x32_bf16 v[50:53], v[154:157], v[170:173], v[50:53]
	v_mfma_f32_16x16x32_bf16 v[46:49], v[146:149], v[178:181], v[46:49]
	v_mfma_f32_16x16x32_bf16 v[42:45], v[154:157], v[178:181], v[42:45]
	v_mfma_f32_16x16x32_bf16 v[38:41], v[146:149], v[186:189], v[38:41]
	v_mfma_f32_16x16x32_bf16 v[34:37], v[154:157], v[186:189], v[34:37]
	v_mfma_f32_16x16x32_bf16 v[62:65], v[150:153], v[166:169], v[62:65]
	v_mfma_f32_16x16x32_bf16 v[58:61], v[158:161], v[166:169], v[58:61]
	v_mfma_f32_16x16x32_bf16 v[54:57], v[150:153], v[174:177], v[54:57]
	v_mfma_f32_16x16x32_bf16 v[50:53], v[158:161], v[174:177], v[50:53]
	v_mfma_f32_16x16x32_bf16 v[46:49], v[150:153], v[182:185], v[46:49]
	v_mfma_f32_16x16x32_bf16 v[42:45], v[158:161], v[182:185], v[42:45]
	v_mfma_f32_16x16x32_bf16 v[38:41], v[150:153], v[190:193], v[38:41]
	v_mfma_f32_16x16x32_bf16 v[34:37], v[158:161], v[190:193], v[34:37]
	s_barrier
	s_add_i32 s52, s52, s8
	s_mov_b32 m0, s52
	ds_read_b128 v[162:165], v239 offset:49152
	ds_read_b128 v[166:169], v239 offset:50176
	ds_read_b128 v[170:173], v239 offset:51200
	ds_read_b128 v[174:177], v239 offset:52224
	ds_read_b128 v[178:181], v239 offset:53248
	ds_read_b128 v[182:185], v239 offset:54272
	ds_read_b128 v[186:189], v239 offset:55296
	ds_read_b128 v[190:193], v239 offset:56320
	global_load_lds_dwordx4 v194, s[50:51]
	s_add_i32 m0, s52, 0x2000
	s_add_u32 s42, s42, 0xe4000
	v_lshl_add_u64 v[208:209], s[50:51], 0, v[196:197]
	s_addc_u32 s43, s43, 0
	s_add_i32 s50, s53, s8
	global_load_lds_dwordx4 v[208:209], off
	s_mov_b32 m0, s50
	s_nop 0
	global_load_lds_dwordx4 v194, s[42:43]
	s_add_i32 m0, s50, 0x2000
	s_nop 0
	global_load_lds_dwordx4 v196, s[42:43]
	s_mov_b64 s[100:101], s[48:49]
	s_waitcnt vmcnt(6) lgkmcnt(0)
	s_barrier
	v_mfma_f32_16x16x32_bf16 v[94:97], v[130:133], v[162:165], v[94:97]
	v_mfma_f32_16x16x32_bf16 v[90:93], v[138:141], v[162:165], v[90:93]
	v_mfma_f32_16x16x32_bf16 v[86:89], v[130:133], v[170:173], v[86:89]
	v_mfma_f32_16x16x32_bf16 v[82:85], v[138:141], v[170:173], v[82:85]
	v_mfma_f32_16x16x32_bf16 v[78:81], v[130:133], v[178:181], v[78:81]
	v_mfma_f32_16x16x32_bf16 v[74:77], v[138:141], v[178:181], v[74:77]
	v_mfma_f32_16x16x32_bf16 v[70:73], v[130:133], v[186:189], v[70:73]
	v_mfma_f32_16x16x32_bf16 v[66:69], v[138:141], v[186:189], v[66:69]
	v_mfma_f32_16x16x32_bf16 v[94:97], v[134:137], v[166:169], v[94:97]
	v_mfma_f32_16x16x32_bf16 v[90:93], v[142:145], v[166:169], v[90:93]
	v_mfma_f32_16x16x32_bf16 v[86:89], v[134:137], v[174:177], v[86:89]
	v_mfma_f32_16x16x32_bf16 v[82:85], v[142:145], v[174:177], v[82:85]
	v_mfma_f32_16x16x32_bf16 v[78:81], v[134:137], v[182:185], v[78:81]
	v_mfma_f32_16x16x32_bf16 v[74:77], v[142:145], v[182:185], v[74:77]
	v_mfma_f32_16x16x32_bf16 v[70:73], v[134:137], v[190:193], v[70:73]
	v_mfma_f32_16x16x32_bf16 v[66:69], v[142:145], v[190:193], v[66:69]
	v_mfma_f32_16x16x32_bf16 v[30:33], v[146:149], v[162:165], v[30:33]
	v_mfma_f32_16x16x32_bf16 v[26:29], v[154:157], v[162:165], v[26:29]
	v_mfma_f32_16x16x32_bf16 v[22:25], v[146:149], v[170:173], v[22:25]
	v_mfma_f32_16x16x32_bf16 v[18:21], v[154:157], v[170:173], v[18:21]
	v_mfma_f32_16x16x32_bf16 v[14:17], v[146:149], v[178:181], v[14:17]
	v_mfma_f32_16x16x32_bf16 v[10:13], v[154:157], v[178:181], v[10:13]
	v_mfma_f32_16x16x32_bf16 v[6:9], v[146:149], v[186:189], v[6:9]
	v_mfma_f32_16x16x32_bf16 v[2:5], v[154:157], v[186:189], v[2:5]
	v_mfma_f32_16x16x32_bf16 v[30:33], v[150:153], v[166:169], v[30:33]
	v_mfma_f32_16x16x32_bf16 v[26:29], v[158:161], v[166:169], v[26:29]
	v_mfma_f32_16x16x32_bf16 v[22:25], v[150:153], v[174:177], v[22:25]
	v_mfma_f32_16x16x32_bf16 v[18:21], v[158:161], v[174:177], v[18:21]
	v_mfma_f32_16x16x32_bf16 v[14:17], v[150:153], v[182:185], v[14:17]
	v_mfma_f32_16x16x32_bf16 v[10:13], v[158:161], v[182:185], v[10:13]
	v_mfma_f32_16x16x32_bf16 v[6:9], v[150:153], v[190:193], v[6:9]
	v_mfma_f32_16x16x32_bf16 v[2:5], v[158:161], v[190:193], v[2:5]
	s_barrier
	s_add_i32 s67, s67, 2
	s_add_u32 s62, s62, 0x1c0000
	s_addc_u32 s63, s63, 0
	s_add_u32 s0, s0, 0x440000
	s_addc_u32 s1, s1, 0
	s_cmp_gt_u32 s67, 29
	s_cbranch_scc0 .LBB0_761
	s_and_b64 vcc, exec, s[26:27]
	s_cbranch_vccz .LBB0_764
	s_barrier

.LBB0_903:
	s_mov_b32 m0, s23
	s_nop 0
	global_load_lds_dwordx4 v194, s[100:101]
	s_mov_b32 m0, s31
	s_nop 0
	global_load_lds_dwordx4 v196, s[100:101]
	ds_read_b128 v[146:149], v225
	ds_read_b128 v[150:153], v225 offset:1024
	ds_read_b128 v[154:157], v225 offset:2048
	ds_read_b128 v[158:161], v225 offset:3072
	ds_read_b128 v[130:133], v227
	ds_read_b128 v[134:137], v227 offset:1024
	ds_read_b128 v[138:141], v227 offset:2048
	ds_read_b128 v[142:145], v227 offset:3072
	v_lshl_add_u64 v[234:235], v[210:211], 0, s[62:63]
	s_add_i32 m0, s8, 0xc000
	s_waitcnt lgkmcnt(0)
	ds_read_b128 v[174:177], v228
	ds_read_b128 v[190:193], v228 offset:1024
	ds_read_b128 v[170:173], v228 offset:2048
	ds_read_b128 v[186:189], v228 offset:3072
	ds_read_b128 v[166:169], v228 offset:4096
	ds_read_b128 v[182:185], v228 offset:5120
	ds_read_b128 v[162:165], v228 offset:6144
	ds_read_b128 v[178:181], v228 offset:7168
	global_load_lds_dwordx4 v[234:235], off
	v_lshl_add_u64 v[234:235], v[212:213], 0, s[62:63]
	s_add_i32 m0, s8, 0xe000
	s_nop 0
	global_load_lds_dwordx4 v[234:235], off
	s_waitcnt vmcnt(8) lgkmcnt(0)
	s_barrier
	v_mfma_f32_16x16x32_bf16 v[126:129], v[146:149], v[174:177], v[126:129]
	v_mfma_f32_16x16x32_bf16 v[122:125], v[154:157], v[174:177], v[122:125]
	v_mfma_f32_16x16x32_bf16 v[118:121], v[146:149], v[170:173], v[118:121]
	v_mfma_f32_16x16x32_bf16 v[114:117], v[154:157], v[170:173], v[114:117]
	v_mfma_f32_16x16x32_bf16 v[110:113], v[146:149], v[166:169], v[110:113]
	v_mfma_f32_16x16x32_bf16 v[106:109], v[154:157], v[166:169], v[106:109]
	v_mfma_f32_16x16x32_bf16 v[102:105], v[146:149], v[162:165], v[102:105]
	v_mfma_f32_16x16x32_bf16 v[98:101], v[154:157], v[162:165], v[98:101]
	v_mfma_f32_16x16x32_bf16 v[126:129], v[150:153], v[190:193], v[126:129]
	v_mfma_f32_16x16x32_bf16 v[122:125], v[158:161], v[190:193], v[122:125]
	v_mfma_f32_16x16x32_bf16 v[118:121], v[150:153], v[186:189], v[118:121]
	v_mfma_f32_16x16x32_bf16 v[114:117], v[158:161], v[186:189], v[114:117]
	v_mfma_f32_16x16x32_bf16 v[110:113], v[150:153], v[182:185], v[110:113]
	v_mfma_f32_16x16x32_bf16 v[106:109], v[158:161], v[182:185], v[106:109]
	v_mfma_f32_16x16x32_bf16 v[102:105], v[150:153], v[178:181], v[102:105]
	v_mfma_f32_16x16x32_bf16 v[98:101], v[158:161], v[178:181], v[98:101]
	v_mfma_f32_16x16x32_bf16 v[94:97], v[130:133], v[174:177], v[94:97]
	v_mfma_f32_16x16x32_bf16 v[90:93], v[138:141], v[174:177], v[90:93]
	v_mfma_f32_16x16x32_bf16 v[86:89], v[130:133], v[170:173], v[86:89]
	v_mfma_f32_16x16x32_bf16 v[82:85], v[138:141], v[170:173], v[82:85]
	v_mfma_f32_16x16x32_bf16 v[78:81], v[130:133], v[166:169], v[78:81]
	v_mfma_f32_16x16x32_bf16 v[74:77], v[138:141], v[166:169], v[74:77]
	v_mfma_f32_16x16x32_bf16 v[70:73], v[130:133], v[162:165], v[70:73]
	v_mfma_f32_16x16x32_bf16 v[66:69], v[138:141], v[162:165], v[66:69]
	v_mfma_f32_16x16x32_bf16 v[94:97], v[134:137], v[190:193], v[94:97]
	v_mfma_f32_16x16x32_bf16 v[90:93], v[142:145], v[190:193], v[90:93]
	v_mfma_f32_16x16x32_bf16 v[86:89], v[134:137], v[186:189], v[86:89]
	v_mfma_f32_16x16x32_bf16 v[82:85], v[142:145], v[186:189], v[82:85]
	v_mfma_f32_16x16x32_bf16 v[78:81], v[134:137], v[182:185], v[78:81]
	v_mfma_f32_16x16x32_bf16 v[74:77], v[142:145], v[182:185], v[74:77]
	v_mfma_f32_16x16x32_bf16 v[70:73], v[134:137], v[178:181], v[70:73]
	v_mfma_f32_16x16x32_bf16 v[66:69], v[142:145], v[178:181], v[66:69]
	s_barrier
	v_cmp_ne_u32_e64 s[42:43], 1, v233
	s_andn2_b64 vcc, exec, s[44:45]
	s_cbranch_vccnz .LBB0_905
	ds_read_b128 v[174:177], v228 offset:16384
	ds_read_b128 v[190:193], v228 offset:17408
	ds_read_b128 v[170:173], v228 offset:18432
	ds_read_b128 v[186:189], v228 offset:19456
	ds_read_b128 v[166:169], v228 offset:20480
	ds_read_b128 v[182:185], v228 offset:21504
	ds_read_b128 v[162:165], v228 offset:22528
	ds_read_b128 v[178:181], v228 offset:23552
.LBB0_905:
	s_add_u32 s68, s0, s62
	s_addc_u32 s69, s1, s63
	s_add_u32 s70, s68, 0x440000
	s_addc_u32 s71, s69, 0
	s_cmp_eq_u32 s62, 0x3fc0000
	s_cselect_b64 s[72:73], -1, 0
	s_and_b64 s[68:69], s[72:73], exec
	s_cselect_b32 s69, s37, s77
	s_cselect_b32 s68, s75, s76
	s_mov_b32 m0, s9
	s_cselect_b32 s71, s35, s71
	s_cselect_b32 s70, s74, s70
	s_add_u32 s80, s68, 0x4000
	global_load_lds_dwordx4 v194, s[68:69]
	s_mov_b32 m0, s10
	s_addc_u32 s81, s69, 0
	global_load_lds_dwordx4 v196, s[68:69]
	s_mov_b32 m0, s11
	s_and_b64 vcc, exec, s[42:43]
	global_load_lds_dwordx4 v194, s[80:81]
	s_mov_b32 m0, s12
	s_nop 0
	global_load_lds_dwordx4 v196, s[80:81]
	s_mov_b64 s[98:99], s[70:71]
	s_waitcnt vmcnt(6) lgkmcnt(0)
	s_barrier
	s_cbranch_vccnz .LBB0_907
	s_waitcnt lgkmcnt(0)
	v_mfma_f32_16x16x32_bf16 v[62:65], v[146:149], v[174:177], v[62:65]
	v_mfma_f32_16x16x32_bf16 v[58:61], v[154:157], v[174:177], v[58:61]
	v_mfma_f32_16x16x32_bf16 v[54:57], v[146:149], v[170:173], v[54:57]
	v_mfma_f32_16x16x32_bf16 v[50:53], v[154:157], v[170:173], v[50:53]
	v_mfma_f32_16x16x32_bf16 v[46:49], v[146:149], v[166:169], v[46:49]
	v_mfma_f32_16x16x32_bf16 v[42:45], v[154:157], v[166:169], v[42:45]
	v_mfma_f32_16x16x32_bf16 v[38:41], v[146:149], v[162:165], v[38:41]
	v_mfma_f32_16x16x32_bf16 v[34:37], v[154:157], v[162:165], v[34:37]
	v_mfma_f32_16x16x32_bf16 v[62:65], v[150:153], v[190:193], v[62:65]
	v_mfma_f32_16x16x32_bf16 v[58:61], v[158:161], v[190:193], v[58:61]
	v_mfma_f32_16x16x32_bf16 v[54:57], v[150:153], v[186:189], v[54:57]
	v_mfma_f32_16x16x32_bf16 v[50:53], v[158:161], v[186:189], v[50:53]
	v_mfma_f32_16x16x32_bf16 v[46:49], v[150:153], v[182:185], v[46:49]
	v_mfma_f32_16x16x32_bf16 v[42:45], v[158:161], v[182:185], v[42:45]
	v_mfma_f32_16x16x32_bf16 v[38:41], v[150:153], v[178:181], v[38:41]
	v_mfma_f32_16x16x32_bf16 v[34:37], v[158:161], v[178:181], v[34:37]
	v_mfma_f32_16x16x32_bf16 v[30:33], v[130:133], v[174:177], v[30:33]
	v_mfma_f32_16x16x32_bf16 v[26:29], v[138:141], v[174:177], v[26:29]
	v_mfma_f32_16x16x32_bf16 v[22:25], v[130:133], v[170:173], v[22:25]
	v_mfma_f32_16x16x32_bf16 v[18:21], v[138:141], v[170:173], v[18:21]
	v_mfma_f32_16x16x32_bf16 v[14:17], v[130:133], v[166:169], v[14:17]
	v_mfma_f32_16x16x32_bf16 v[10:13], v[138:141], v[166:169], v[10:13]
	v_mfma_f32_16x16x32_bf16 v[6:9], v[130:133], v[162:165], v[6:9]
	v_mfma_f32_16x16x32_bf16 v[2:5], v[138:141], v[162:165], v[2:5]
	v_mfma_f32_16x16x32_bf16 v[30:33], v[134:137], v[190:193], v[30:33]
	v_mfma_f32_16x16x32_bf16 v[26:29], v[142:145], v[190:193], v[26:29]
	v_mfma_f32_16x16x32_bf16 v[22:25], v[134:137], v[186:189], v[22:25]
	v_mfma_f32_16x16x32_bf16 v[18:21], v[142:145], v[186:189], v[18:21]
	v_mfma_f32_16x16x32_bf16 v[14:17], v[134:137], v[182:185], v[14:17]
	v_mfma_f32_16x16x32_bf16 v[10:13], v[142:145], v[182:185], v[10:13]
	v_mfma_f32_16x16x32_bf16 v[6:9], v[134:137], v[178:181], v[6:9]
	v_mfma_f32_16x16x32_bf16 v[2:5], v[142:145], v[178:181], v[2:5]
.LBB0_907:
	s_and_b64 vcc, s[40:41], s[72:73]
	v_cndmask_b32_e64 v131, v209, 0, vcc
	v_cndmask_b32_e32 v130, v208, v198, vcc
	v_lshl_add_u64 v[234:235], s[70:71], 0, v[130:131]
	s_barrier
	s_mov_b32 m0, s8
	s_nop 0
	global_load_lds_dwordx4 v194, s[98:99]
	s_mov_b32 m0, s13
	s_nop 0
	global_load_lds_dwordx4 v196, s[98:99]
	v_add_u32_e32 v130, 0x18000, v224
	v_add_u32_e32 v142, 0x1c000, v224
	ds_read_b128 v[146:149], v130
	ds_read_b128 v[150:153], v130 offset:1024
	ds_read_b128 v[154:157], v130 offset:2048
	ds_read_b128 v[158:161], v130 offset:3072
	ds_read_b128 v[130:133], v142
	ds_read_b128 v[134:137], v142 offset:1024
	ds_read_b128 v[138:141], v142 offset:2048
	ds_read_b128 v[142:145], v142 offset:3072
	s_mov_b32 m0, s14
	v_lshl_add_u64 v[236:237], v[234:235], 0, v[194:195]
	s_waitcnt lgkmcnt(0)
	ds_read_b128 v[174:177], v228 offset:32768
	ds_read_b128 v[190:193], v228 offset:33792
	ds_read_b128 v[170:173], v228 offset:34816
	ds_read_b128 v[186:189], v228 offset:35840
	ds_read_b128 v[166:169], v228 offset:36864
	ds_read_b128 v[182:185], v228 offset:37888
	ds_read_b128 v[162:165], v228 offset:38912
	ds_read_b128 v[178:181], v228 offset:39936
	global_load_lds_dwordx4 v[236:237], off
	v_lshl_add_u64 v[234:235], v[234:235], 0, v[196:197]
	s_mov_b32 m0, s15
	s_nop 0
	global_load_lds_dwordx4 v[234:235], off
	s_waitcnt vmcnt(8) lgkmcnt(0)
	s_barrier
	v_mfma_f32_16x16x32_bf16 v[126:129], v[146:149], v[174:177], v[126:129]
	v_mfma_f32_16x16x32_bf16 v[122:125], v[154:157], v[174:177], v[122:125]
	v_mfma_f32_16x16x32_bf16 v[118:121], v[146:149], v[170:173], v[118:121]
	v_mfma_f32_16x16x32_bf16 v[114:117], v[154:157], v[170:173], v[114:117]
	v_mfma_f32_16x16x32_bf16 v[110:113], v[146:149], v[166:169], v[110:113]
	v_mfma_f32_16x16x32_bf16 v[106:109], v[154:157], v[166:169], v[106:109]
	v_mfma_f32_16x16x32_bf16 v[102:105], v[146:149], v[162:165], v[102:105]
	v_mfma_f32_16x16x32_bf16 v[98:101], v[154:157], v[162:165], v[98:101]
	v_mfma_f32_16x16x32_bf16 v[126:129], v[150:153], v[190:193], v[126:129]
	v_mfma_f32_16x16x32_bf16 v[122:125], v[158:161], v[190:193], v[122:125]
	v_mfma_f32_16x16x32_bf16 v[118:121], v[150:153], v[186:189], v[118:121]
	v_mfma_f32_16x16x32_bf16 v[114:117], v[158:161], v[186:189], v[114:117]
	v_mfma_f32_16x16x32_bf16 v[110:113], v[150:153], v[182:185], v[110:113]
	v_mfma_f32_16x16x32_bf16 v[106:109], v[158:161], v[182:185], v[106:109]
	v_mfma_f32_16x16x32_bf16 v[102:105], v[150:153], v[178:181], v[102:105]
	v_mfma_f32_16x16x32_bf16 v[98:101], v[158:161], v[178:181], v[98:101]
	v_mfma_f32_16x16x32_bf16 v[94:97], v[130:133], v[174:177], v[94:97]
	v_mfma_f32_16x16x32_bf16 v[90:93], v[138:141], v[174:177], v[90:93]
	v_mfma_f32_16x16x32_bf16 v[86:89], v[130:133], v[170:173], v[86:89]
	v_mfma_f32_16x16x32_bf16 v[82:85], v[138:141], v[170:173], v[82:85]
	v_mfma_f32_16x16x32_bf16 v[78:81], v[130:133], v[166:169], v[78:81]
	v_mfma_f32_16x16x32_bf16 v[74:77], v[138:141], v[166:169], v[74:77]
	v_mfma_f32_16x16x32_bf16 v[70:73], v[130:133], v[162:165], v[70:73]
	v_mfma_f32_16x16x32_bf16 v[66:69], v[138:141], v[162:165], v[66:69]
	v_mfma_f32_16x16x32_bf16 v[94:97], v[134:137], v[190:193], v[94:97]
	v_mfma_f32_16x16x32_bf16 v[90:93], v[142:145], v[190:193], v[90:93]
	v_mfma_f32_16x16x32_bf16 v[86:89], v[134:137], v[186:189], v[86:89]
	v_mfma_f32_16x16x32_bf16 v[82:85], v[142:145], v[186:189], v[82:85]
	v_mfma_f32_16x16x32_bf16 v[78:81], v[134:137], v[182:185], v[78:81]
	v_mfma_f32_16x16x32_bf16 v[74:77], v[142:145], v[182:185], v[74:77]
	v_mfma_f32_16x16x32_bf16 v[70:73], v[134:137], v[178:181], v[70:73]
	v_mfma_f32_16x16x32_bf16 v[66:69], v[142:145], v[178:181], v[66:69]
	s_barrier
	s_and_b64 vcc, exec, s[42:43]
	s_cbranch_vccnz .LBB0_909
	ds_read_b128 v[174:177], v228 offset:49152
	ds_read_b128 v[190:193], v228 offset:50176
	ds_read_b128 v[170:173], v228 offset:51200
	ds_read_b128 v[186:189], v228 offset:52224
	ds_read_b128 v[166:169], v228 offset:53248
	ds_read_b128 v[182:185], v228 offset:54272
	ds_read_b128 v[162:165], v228 offset:55296
	ds_read_b128 v[178:181], v228 offset:56320
.LBB0_909:
	s_add_u32 s72, s68, 0xe0000
	s_addc_u32 s73, s69, 0
	s_add_u32 s70, s70, 0x220000
	s_addc_u32 s71, s71, 0
	s_mov_b32 m0, s16
	s_add_u32 s68, s68, 0xe4000
	global_load_lds_dwordx4 v194, s[72:73]
	s_mov_b32 m0, s17
	s_addc_u32 s69, s69, 0
	global_load_lds_dwordx4 v196, s[72:73]
	s_mov_b32 m0, s54
	s_and_b64 vcc, exec, s[42:43]
	global_load_lds_dwordx4 v194, s[68:69]
	s_mov_b32 m0, s55
	s_nop 0
	global_load_lds_dwordx4 v196, s[68:69]
	s_mov_b64 s[100:101], s[70:71]
	s_waitcnt vmcnt(6) lgkmcnt(0)
	s_barrier
	s_cbranch_vccnz .LBB0_902
	s_waitcnt lgkmcnt(0)
	v_mfma_f32_16x16x32_bf16 v[62:65], v[146:149], v[174:177], v[62:65]
	v_mfma_f32_16x16x32_bf16 v[58:61], v[154:157], v[174:177], v[58:61]
	v_mfma_f32_16x16x32_bf16 v[54:57], v[146:149], v[170:173], v[54:57]
	v_mfma_f32_16x16x32_bf16 v[50:53], v[154:157], v[170:173], v[50:53]
	v_mfma_f32_16x16x32_bf16 v[46:49], v[146:149], v[166:169], v[46:49]
	v_mfma_f32_16x16x32_bf16 v[42:45], v[154:157], v[166:169], v[42:45]
	v_mfma_f32_16x16x32_bf16 v[38:41], v[146:149], v[162:165], v[38:41]
	v_mfma_f32_16x16x32_bf16 v[34:37], v[154:157], v[162:165], v[34:37]
	v_mfma_f32_16x16x32_bf16 v[62:65], v[150:153], v[190:193], v[62:65]
	v_mfma_f32_16x16x32_bf16 v[58:61], v[158:161], v[190:193], v[58:61]
	v_mfma_f32_16x16x32_bf16 v[54:57], v[150:153], v[186:189], v[54:57]
	v_mfma_f32_16x16x32_bf16 v[50:53], v[158:161], v[186:189], v[50:53]
	v_mfma_f32_16x16x32_bf16 v[46:49], v[150:153], v[182:185], v[46:49]
	v_mfma_f32_16x16x32_bf16 v[42:45], v[158:161], v[182:185], v[42:45]
	v_mfma_f32_16x16x32_bf16 v[38:41], v[150:153], v[178:181], v[38:41]
	v_mfma_f32_16x16x32_bf16 v[34:37], v[158:161], v[178:181], v[34:37]
	v_mfma_f32_16x16x32_bf16 v[30:33], v[130:133], v[174:177], v[30:33]
	v_mfma_f32_16x16x32_bf16 v[26:29], v[138:141], v[174:177], v[26:29]
	v_mfma_f32_16x16x32_bf16 v[22:25], v[130:133], v[170:173], v[22:25]
	v_mfma_f32_16x16x32_bf16 v[18:21], v[138:141], v[170:173], v[18:21]
	v_mfma_f32_16x16x32_bf16 v[14:17], v[130:133], v[166:169], v[14:17]
	v_mfma_f32_16x16x32_bf16 v[10:13], v[138:141], v[166:169], v[10:13]
	v_mfma_f32_16x16x32_bf16 v[6:9], v[130:133], v[162:165], v[6:9]
	v_mfma_f32_16x16x32_bf16 v[2:5], v[138:141], v[162:165], v[2:5]
	v_mfma_f32_16x16x32_bf16 v[30:33], v[134:137], v[190:193], v[30:33]
	v_mfma_f32_16x16x32_bf16 v[26:29], v[142:145], v[190:193], v[26:29]
	v_mfma_f32_16x16x32_bf16 v[22:25], v[134:137], v[186:189], v[22:25]
	v_mfma_f32_16x16x32_bf16 v[18:21], v[142:145], v[186:189], v[18:21]
	v_mfma_f32_16x16x32_bf16 v[14:17], v[134:137], v[182:185], v[14:17]
	v_mfma_f32_16x16x32_bf16 v[10:13], v[142:145], v[182:185], v[10:13]
	v_mfma_f32_16x16x32_bf16 v[6:9], v[134:137], v[178:181], v[6:9]
	v_mfma_f32_16x16x32_bf16 v[2:5], v[142:145], v[178:181], v[2:5]
	s_branch .LBB0_902

.LBB0_1289:
	s_mov_b32 m0, s27
	s_nop 0
	global_load_lds_dwordx4 v194, s[100:101]
	s_mov_b32 m0, s54
	s_nop 0
	global_load_lds_dwordx4 v196, s[100:101]
	v_add_u32_e32 v142, 0x14000, v229
	ds_read_b128 v[146:149], v230
	ds_read_b128 v[150:153], v230 offset:1024
	ds_read_b128 v[154:157], v230 offset:2048
	ds_read_b128 v[158:161], v230 offset:3072
	ds_read_b128 v[130:133], v142
	ds_read_b128 v[134:137], v142 offset:1024
	ds_read_b128 v[138:141], v142 offset:2048
	ds_read_b128 v[142:145], v142 offset:3072
	v_lshl_add_u64 v[234:235], v[222:223], 0, s[48:49]
	s_add_i32 m0, s8, 0xc000
	s_waitcnt lgkmcnt(0)
	ds_read_b128 v[174:177], v231
	ds_read_b128 v[190:193], v231 offset:1024
	ds_read_b128 v[170:173], v231 offset:2048
	ds_read_b128 v[186:189], v231 offset:3072
	ds_read_b128 v[166:169], v231 offset:4096
	ds_read_b128 v[182:185], v231 offset:5120
	ds_read_b128 v[162:165], v231 offset:6144
	ds_read_b128 v[178:181], v231 offset:7168
	global_load_lds_dwordx4 v[234:235], off
	v_lshl_add_u64 v[234:235], v[224:225], 0, s[48:49]
	s_add_i32 m0, s8, 0xe000
	s_nop 0
	global_load_lds_dwordx4 v[234:235], off
	s_waitcnt vmcnt(8) lgkmcnt(0)
	s_barrier
	v_mfma_f32_16x16x32_bf16 v[126:129], v[146:149], v[174:177], v[126:129]
	v_mfma_f32_16x16x32_bf16 v[122:125], v[154:157], v[174:177], v[122:125]
	v_mfma_f32_16x16x32_bf16 v[118:121], v[146:149], v[170:173], v[118:121]
	v_mfma_f32_16x16x32_bf16 v[110:113], v[154:157], v[170:173], v[110:113]
	v_mfma_f32_16x16x32_bf16 v[102:105], v[146:149], v[166:169], v[102:105]
	v_mfma_f32_16x16x32_bf16 v[94:97], v[154:157], v[166:169], v[94:97]
	v_mfma_f32_16x16x32_bf16 v[86:89], v[146:149], v[162:165], v[86:89]
	v_mfma_f32_16x16x32_bf16 v[78:81], v[154:157], v[162:165], v[78:81]
	v_mfma_f32_16x16x32_bf16 v[126:129], v[150:153], v[190:193], v[126:129]
	v_mfma_f32_16x16x32_bf16 v[122:125], v[158:161], v[190:193], v[122:125]
	v_mfma_f32_16x16x32_bf16 v[118:121], v[150:153], v[186:189], v[118:121]
	v_mfma_f32_16x16x32_bf16 v[110:113], v[158:161], v[186:189], v[110:113]
	v_mfma_f32_16x16x32_bf16 v[102:105], v[150:153], v[182:185], v[102:105]
	v_mfma_f32_16x16x32_bf16 v[94:97], v[158:161], v[182:185], v[94:97]
	v_mfma_f32_16x16x32_bf16 v[86:89], v[150:153], v[178:181], v[86:89]
	v_mfma_f32_16x16x32_bf16 v[78:81], v[158:161], v[178:181], v[78:81]
	v_mfma_f32_16x16x32_bf16 v[114:117], v[130:133], v[174:177], v[114:117]
	v_mfma_f32_16x16x32_bf16 v[106:109], v[138:141], v[174:177], v[106:109]
	v_mfma_f32_16x16x32_bf16 v[98:101], v[130:133], v[170:173], v[98:101]
	v_mfma_f32_16x16x32_bf16 v[90:93], v[138:141], v[170:173], v[90:93]
	v_mfma_f32_16x16x32_bf16 v[82:85], v[130:133], v[166:169], v[82:85]
	v_mfma_f32_16x16x32_bf16 v[74:77], v[138:141], v[166:169], v[74:77]
	v_mfma_f32_16x16x32_bf16 v[70:73], v[130:133], v[162:165], v[70:73]
	v_mfma_f32_16x16x32_bf16 v[66:69], v[138:141], v[162:165], v[66:69]
	v_mfma_f32_16x16x32_bf16 v[114:117], v[134:137], v[190:193], v[114:117]
	v_mfma_f32_16x16x32_bf16 v[106:109], v[142:145], v[190:193], v[106:109]
	v_mfma_f32_16x16x32_bf16 v[98:101], v[134:137], v[186:189], v[98:101]
	v_mfma_f32_16x16x32_bf16 v[90:93], v[142:145], v[186:189], v[90:93]
	v_mfma_f32_16x16x32_bf16 v[82:85], v[134:137], v[182:185], v[82:85]
	v_mfma_f32_16x16x32_bf16 v[74:77], v[142:145], v[182:185], v[74:77]
	v_mfma_f32_16x16x32_bf16 v[70:73], v[134:137], v[178:181], v[70:73]
	v_mfma_f32_16x16x32_bf16 v[66:69], v[142:145], v[178:181], v[66:69]
	s_barrier
	s_andn2_b64 s[42:43], exec, s[40:41]
	s_andn2_b64 vcc, exec, s[40:41]
	s_cbranch_vccnz .LBB0_1291
	ds_read_b128 v[174:177], v231 offset:16384
	ds_read_b128 v[190:193], v231 offset:17408
	ds_read_b128 v[170:173], v231 offset:18432
	ds_read_b128 v[186:189], v231 offset:19456
	ds_read_b128 v[166:169], v231 offset:20480
	ds_read_b128 v[182:185], v231 offset:21504
	ds_read_b128 v[162:165], v231 offset:22528
	ds_read_b128 v[178:181], v231 offset:23552
.LBB0_1291:
	s_add_u32 s52, s36, s48
	s_addc_u32 s53, s37, s49
	s_add_u32 s56, s52, 0x440000
	s_addc_u32 s57, s53, 0
	s_cmp_eq_u32 s48, 0x3fc0000
	s_cselect_b64 s[58:59], -1, 0
	s_and_b64 s[52:53], s[58:59], exec
	s_cselect_b32 s53, s31, s63
	s_cselect_b32 s52, s61, s62
	s_mov_b32 m0, s9
	s_cselect_b32 s57, s19, s57
	s_cselect_b32 s56, s29, s56
	s_add_u32 s68, s52, 0x4000
	global_load_lds_dwordx4 v194, s[52:53]
	s_mov_b32 m0, s10
	s_addc_u32 s69, s53, 0
	global_load_lds_dwordx4 v196, s[52:53]
	s_mov_b32 m0, s11
	s_and_b64 vcc, exec, s[42:43]
	global_load_lds_dwordx4 v194, s[68:69]
	s_mov_b32 m0, s12
	s_nop 0
	global_load_lds_dwordx4 v196, s[68:69]
	s_mov_b64 s[98:99], s[56:57]
	s_waitcnt vmcnt(6) lgkmcnt(0)
	s_barrier
	s_cbranch_vccnz .LBB0_1293
	s_waitcnt lgkmcnt(0)
	v_mfma_f32_16x16x32_bf16 v[62:65], v[146:149], v[174:177], v[62:65]
	v_mfma_f32_16x16x32_bf16 v[58:61], v[154:157], v[174:177], v[58:61]
	v_mfma_f32_16x16x32_bf16 v[46:49], v[146:149], v[170:173], v[46:49]
	v_mfma_f32_16x16x32_bf16 v[42:45], v[154:157], v[170:173], v[42:45]
	v_mfma_f32_16x16x32_bf16 v[30:33], v[146:149], v[166:169], v[30:33]
	v_mfma_f32_16x16x32_bf16 v[26:29], v[154:157], v[166:169], v[26:29]
	v_mfma_f32_16x16x32_bf16 v[14:17], v[146:149], v[162:165], v[14:17]
	v_mfma_f32_16x16x32_bf16 v[10:13], v[154:157], v[162:165], v[10:13]
	v_mfma_f32_16x16x32_bf16 v[62:65], v[150:153], v[190:193], v[62:65]
	v_mfma_f32_16x16x32_bf16 v[58:61], v[158:161], v[190:193], v[58:61]
	v_mfma_f32_16x16x32_bf16 v[46:49], v[150:153], v[186:189], v[46:49]
	v_mfma_f32_16x16x32_bf16 v[42:45], v[158:161], v[186:189], v[42:45]
	v_mfma_f32_16x16x32_bf16 v[30:33], v[150:153], v[182:185], v[30:33]
	v_mfma_f32_16x16x32_bf16 v[26:29], v[158:161], v[182:185], v[26:29]
	v_mfma_f32_16x16x32_bf16 v[14:17], v[150:153], v[178:181], v[14:17]
	v_mfma_f32_16x16x32_bf16 v[10:13], v[158:161], v[178:181], v[10:13]
	v_mfma_f32_16x16x32_bf16 v[54:57], v[130:133], v[174:177], v[54:57]
	v_mfma_f32_16x16x32_bf16 v[50:53], v[138:141], v[174:177], v[50:53]
	v_mfma_f32_16x16x32_bf16 v[38:41], v[130:133], v[170:173], v[38:41]
	v_mfma_f32_16x16x32_bf16 v[34:37], v[138:141], v[170:173], v[34:37]
	v_mfma_f32_16x16x32_bf16 v[22:25], v[130:133], v[166:169], v[22:25]
	v_mfma_f32_16x16x32_bf16 v[18:21], v[138:141], v[166:169], v[18:21]
	v_mfma_f32_16x16x32_bf16 v[6:9], v[130:133], v[162:165], v[6:9]
	v_mfma_f32_16x16x32_bf16 v[2:5], v[138:141], v[162:165], v[2:5]
	v_mfma_f32_16x16x32_bf16 v[54:57], v[134:137], v[190:193], v[54:57]
	v_mfma_f32_16x16x32_bf16 v[50:53], v[142:145], v[190:193], v[50:53]
	v_mfma_f32_16x16x32_bf16 v[38:41], v[134:137], v[186:189], v[38:41]
	v_mfma_f32_16x16x32_bf16 v[34:37], v[142:145], v[186:189], v[34:37]
	v_mfma_f32_16x16x32_bf16 v[22:25], v[134:137], v[182:185], v[22:25]
	v_mfma_f32_16x16x32_bf16 v[18:21], v[142:145], v[182:185], v[18:21]
	v_mfma_f32_16x16x32_bf16 v[6:9], v[134:137], v[178:181], v[6:9]
	v_mfma_f32_16x16x32_bf16 v[2:5], v[142:145], v[178:181], v[2:5]
.LBB0_1293:
	s_and_b64 vcc, s[34:35], s[58:59]
	v_cndmask_b32_e64 v131, v221, 0, vcc
	v_cndmask_b32_e32 v130, v220, v198, vcc
	v_lshl_add_u64 v[234:235], s[56:57], 0, v[130:131]
	s_barrier
	s_mov_b32 m0, s8
	s_nop 0
	global_load_lds_dwordx4 v194, s[98:99]
	s_mov_b32 m0, s13
	s_nop 0
	global_load_lds_dwordx4 v196, s[98:99]
	v_add_u32_e32 v130, 0x18000, v229
	v_add_u32_e32 v142, 0x1c000, v229
	ds_read_b128 v[146:149], v130
	ds_read_b128 v[150:153], v130 offset:1024
	ds_read_b128 v[154:157], v130 offset:2048
	ds_read_b128 v[158:161], v130 offset:3072
	ds_read_b128 v[130:133], v142
	ds_read_b128 v[134:137], v142 offset:1024
	ds_read_b128 v[138:141], v142 offset:2048
	ds_read_b128 v[142:145], v142 offset:3072
	s_mov_b32 m0, s14
	v_lshl_add_u64 v[236:237], v[234:235], 0, v[194:195]
	s_waitcnt lgkmcnt(0)
	ds_read_b128 v[174:177], v231 offset:32768
	ds_read_b128 v[190:193], v231 offset:33792
	ds_read_b128 v[170:173], v231 offset:34816
	ds_read_b128 v[186:189], v231 offset:35840
	ds_read_b128 v[166:169], v231 offset:36864
	ds_read_b128 v[182:185], v231 offset:37888
	ds_read_b128 v[162:165], v231 offset:38912
	ds_read_b128 v[178:181], v231 offset:39936
	global_load_lds_dwordx4 v[236:237], off
	v_lshl_add_u64 v[234:235], v[234:235], 0, v[196:197]
	s_mov_b32 m0, s15
	s_nop 0
	global_load_lds_dwordx4 v[234:235], off
	s_waitcnt vmcnt(8) lgkmcnt(0)
	s_barrier
	v_mfma_f32_16x16x32_bf16 v[126:129], v[146:149], v[174:177], v[126:129]
	v_mfma_f32_16x16x32_bf16 v[122:125], v[154:157], v[174:177], v[122:125]
	v_mfma_f32_16x16x32_bf16 v[118:121], v[146:149], v[170:173], v[118:121]
	v_mfma_f32_16x16x32_bf16 v[110:113], v[154:157], v[170:173], v[110:113]
	v_mfma_f32_16x16x32_bf16 v[102:105], v[146:149], v[166:169], v[102:105]
	v_mfma_f32_16x16x32_bf16 v[94:97], v[154:157], v[166:169], v[94:97]
	v_mfma_f32_16x16x32_bf16 v[86:89], v[146:149], v[162:165], v[86:89]
	v_mfma_f32_16x16x32_bf16 v[78:81], v[154:157], v[162:165], v[78:81]
	v_mfma_f32_16x16x32_bf16 v[126:129], v[150:153], v[190:193], v[126:129]
	v_mfma_f32_16x16x32_bf16 v[122:125], v[158:161], v[190:193], v[122:125]
	v_mfma_f32_16x16x32_bf16 v[118:121], v[150:153], v[186:189], v[118:121]
	v_mfma_f32_16x16x32_bf16 v[110:113], v[158:161], v[186:189], v[110:113]
	v_mfma_f32_16x16x32_bf16 v[102:105], v[150:153], v[182:185], v[102:105]
	v_mfma_f32_16x16x32_bf16 v[94:97], v[158:161], v[182:185], v[94:97]
	v_mfma_f32_16x16x32_bf16 v[86:89], v[150:153], v[178:181], v[86:89]
	v_mfma_f32_16x16x32_bf16 v[78:81], v[158:161], v[178:181], v[78:81]
	v_mfma_f32_16x16x32_bf16 v[114:117], v[130:133], v[174:177], v[114:117]
	v_mfma_f32_16x16x32_bf16 v[106:109], v[138:141], v[174:177], v[106:109]
	v_mfma_f32_16x16x32_bf16 v[98:101], v[130:133], v[170:173], v[98:101]
	v_mfma_f32_16x16x32_bf16 v[90:93], v[138:141], v[170:173], v[90:93]
	v_mfma_f32_16x16x32_bf16 v[82:85], v[130:133], v[166:169], v[82:85]
	v_mfma_f32_16x16x32_bf16 v[74:77], v[138:141], v[166:169], v[74:77]
	v_mfma_f32_16x16x32_bf16 v[70:73], v[130:133], v[162:165], v[70:73]
	v_mfma_f32_16x16x32_bf16 v[66:69], v[138:141], v[162:165], v[66:69]
	v_mfma_f32_16x16x32_bf16 v[114:117], v[134:137], v[190:193], v[114:117]
	v_mfma_f32_16x16x32_bf16 v[106:109], v[142:145], v[190:193], v[106:109]
	v_mfma_f32_16x16x32_bf16 v[98:101], v[134:137], v[186:189], v[98:101]
	v_mfma_f32_16x16x32_bf16 v[90:93], v[142:145], v[186:189], v[90:93]
	v_mfma_f32_16x16x32_bf16 v[82:85], v[134:137], v[182:185], v[82:85]
	v_mfma_f32_16x16x32_bf16 v[74:77], v[142:145], v[182:185], v[74:77]
	v_mfma_f32_16x16x32_bf16 v[70:73], v[134:137], v[178:181], v[70:73]
	v_mfma_f32_16x16x32_bf16 v[66:69], v[142:145], v[178:181], v[66:69]
	s_barrier
	s_and_b64 vcc, exec, s[42:43]
	s_cbranch_vccnz .LBB0_1295
	ds_read_b128 v[174:177], v231 offset:49152
	ds_read_b128 v[190:193], v231 offset:50176
	ds_read_b128 v[170:173], v231 offset:51200
	ds_read_b128 v[186:189], v231 offset:52224
	ds_read_b128 v[166:169], v231 offset:53248
	ds_read_b128 v[182:185], v231 offset:54272
	ds_read_b128 v[162:165], v231 offset:55296
	ds_read_b128 v[178:181], v231 offset:56320
.LBB0_1295:
	s_add_u32 s58, s52, 0x40000
	s_addc_u32 s59, s53, 0
	s_add_u32 s56, s56, 0x220000
	s_addc_u32 s57, s57, 0
	s_mov_b32 m0, s16
	s_add_u32 s52, s52, 0x44000
	global_load_lds_dwordx4 v194, s[58:59]
	s_mov_b32 m0, s17
	s_addc_u32 s53, s53, 0
	global_load_lds_dwordx4 v196, s[58:59]
	s_mov_b32 m0, s55
	s_and_b64 vcc, exec, s[42:43]
	global_load_lds_dwordx4 v194, s[52:53]
	s_mov_b32 m0, s60
	s_nop 0
	global_load_lds_dwordx4 v196, s[52:53]
	s_mov_b64 s[100:101], s[56:57]
	s_waitcnt vmcnt(6) lgkmcnt(0)
	s_barrier
	s_cbranch_vccnz .LBB0_1288
	s_waitcnt lgkmcnt(0)
	v_mfma_f32_16x16x32_bf16 v[62:65], v[146:149], v[174:177], v[62:65]
	v_mfma_f32_16x16x32_bf16 v[58:61], v[154:157], v[174:177], v[58:61]
	v_mfma_f32_16x16x32_bf16 v[46:49], v[146:149], v[170:173], v[46:49]
	v_mfma_f32_16x16x32_bf16 v[42:45], v[154:157], v[170:173], v[42:45]
	v_mfma_f32_16x16x32_bf16 v[30:33], v[146:149], v[166:169], v[30:33]
	v_mfma_f32_16x16x32_bf16 v[26:29], v[154:157], v[166:169], v[26:29]
	v_mfma_f32_16x16x32_bf16 v[14:17], v[146:149], v[162:165], v[14:17]
	v_mfma_f32_16x16x32_bf16 v[10:13], v[154:157], v[162:165], v[10:13]
	v_mfma_f32_16x16x32_bf16 v[62:65], v[150:153], v[190:193], v[62:65]
	v_mfma_f32_16x16x32_bf16 v[58:61], v[158:161], v[190:193], v[58:61]
	v_mfma_f32_16x16x32_bf16 v[46:49], v[150:153], v[186:189], v[46:49]
	v_mfma_f32_16x16x32_bf16 v[42:45], v[158:161], v[186:189], v[42:45]
	v_mfma_f32_16x16x32_bf16 v[30:33], v[150:153], v[182:185], v[30:33]
	v_mfma_f32_16x16x32_bf16 v[26:29], v[158:161], v[182:185], v[26:29]
	v_mfma_f32_16x16x32_bf16 v[14:17], v[150:153], v[178:181], v[14:17]
	v_mfma_f32_16x16x32_bf16 v[10:13], v[158:161], v[178:181], v[10:13]
	v_mfma_f32_16x16x32_bf16 v[54:57], v[130:133], v[174:177], v[54:57]
	v_mfma_f32_16x16x32_bf16 v[50:53], v[138:141], v[174:177], v[50:53]
	v_mfma_f32_16x16x32_bf16 v[38:41], v[130:133], v[170:173], v[38:41]
	v_mfma_f32_16x16x32_bf16 v[34:37], v[138:141], v[170:173], v[34:37]
	v_mfma_f32_16x16x32_bf16 v[22:25], v[130:133], v[166:169], v[22:25]
	v_mfma_f32_16x16x32_bf16 v[18:21], v[138:141], v[166:169], v[18:21]
	v_mfma_f32_16x16x32_bf16 v[6:9], v[130:133], v[162:165], v[6:9]
	v_mfma_f32_16x16x32_bf16 v[2:5], v[138:141], v[162:165], v[2:5]
	v_mfma_f32_16x16x32_bf16 v[54:57], v[134:137], v[190:193], v[54:57]
	v_mfma_f32_16x16x32_bf16 v[50:53], v[142:145], v[190:193], v[50:53]
	v_mfma_f32_16x16x32_bf16 v[38:41], v[134:137], v[186:189], v[38:41]
	v_mfma_f32_16x16x32_bf16 v[34:37], v[142:145], v[186:189], v[34:37]
	v_mfma_f32_16x16x32_bf16 v[22:25], v[134:137], v[182:185], v[22:25]
	v_mfma_f32_16x16x32_bf16 v[18:21], v[142:145], v[182:185], v[18:21]
	v_mfma_f32_16x16x32_bf16 v[6:9], v[134:137], v[178:181], v[6:9]
	v_mfma_f32_16x16x32_bf16 v[2:5], v[142:145], v[178:181], v[2:5]
	s_branch .LBB0_1288

.LBB0_1612:
	s_mov_b32 m0, s54
	s_nop 0
	global_load_lds_dwordx4 v194, s[100:101]
	s_mov_b32 m0, s55
	s_nop 0
	global_load_lds_dwordx4 v196, s[100:101]
	v_add_u32_e32 v1, 0x10000, v232
	ds_read_b128 v[146:149], v1
	ds_read_b128 v[150:153], v1 offset:1024
	ds_read_b128 v[154:157], v1 offset:2048
	ds_read_b128 v[158:161], v1 offset:3072
	v_add_u32_e32 v1, 0x14000, v232
	ds_read_b128 v[130:133], v1
	ds_read_b128 v[134:137], v1 offset:1024
	ds_read_b128 v[138:141], v1 offset:2048
	ds_read_b128 v[142:145], v1 offset:3072
	v_lshl_add_u64 v[236:237], v[226:227], 0, s[48:49]
	s_add_i32 m0, s9, 0xc000
	s_waitcnt lgkmcnt(0)
	ds_read_b128 v[174:177], v233
	ds_read_b128 v[190:193], v233 offset:1024
	ds_read_b128 v[170:173], v233 offset:2048
	ds_read_b128 v[186:189], v233 offset:3072
	ds_read_b128 v[166:169], v233 offset:4096
	ds_read_b128 v[182:185], v233 offset:5120
	ds_read_b128 v[162:165], v233 offset:6144
	ds_read_b128 v[178:181], v233 offset:7168
	global_load_lds_dwordx4 v[236:237], off
	v_lshl_add_u64 v[236:237], v[228:229], 0, s[48:49]
	s_add_i32 m0, s9, 0xe000
	s_nop 0
	global_load_lds_dwordx4 v[236:237], off
	s_waitcnt vmcnt(8) lgkmcnt(0)
	s_barrier
	v_mfma_f32_16x16x32_bf16 v[126:129], v[146:149], v[174:177], v[126:129]
	v_mfma_f32_16x16x32_bf16 v[122:125], v[154:157], v[174:177], v[122:125]
	v_mfma_f32_16x16x32_bf16 v[118:121], v[146:149], v[170:173], v[118:121]
	v_mfma_f32_16x16x32_bf16 v[110:113], v[154:157], v[170:173], v[110:113]
	v_mfma_f32_16x16x32_bf16 v[102:105], v[146:149], v[166:169], v[102:105]
	v_mfma_f32_16x16x32_bf16 v[94:97], v[154:157], v[166:169], v[94:97]
	v_mfma_f32_16x16x32_bf16 v[86:89], v[146:149], v[162:165], v[86:89]
	v_mfma_f32_16x16x32_bf16 v[78:81], v[154:157], v[162:165], v[78:81]
	v_mfma_f32_16x16x32_bf16 v[126:129], v[150:153], v[190:193], v[126:129]
	v_mfma_f32_16x16x32_bf16 v[122:125], v[158:161], v[190:193], v[122:125]
	v_mfma_f32_16x16x32_bf16 v[118:121], v[150:153], v[186:189], v[118:121]
	v_mfma_f32_16x16x32_bf16 v[110:113], v[158:161], v[186:189], v[110:113]
	v_mfma_f32_16x16x32_bf16 v[102:105], v[150:153], v[182:185], v[102:105]
	v_mfma_f32_16x16x32_bf16 v[94:97], v[158:161], v[182:185], v[94:97]
	v_mfma_f32_16x16x32_bf16 v[86:89], v[150:153], v[178:181], v[86:89]
	v_mfma_f32_16x16x32_bf16 v[78:81], v[158:161], v[178:181], v[78:81]
	v_mfma_f32_16x16x32_bf16 v[114:117], v[130:133], v[174:177], v[114:117]
	v_mfma_f32_16x16x32_bf16 v[106:109], v[138:141], v[174:177], v[106:109]
	v_mfma_f32_16x16x32_bf16 v[98:101], v[130:133], v[170:173], v[98:101]
	v_mfma_f32_16x16x32_bf16 v[90:93], v[138:141], v[170:173], v[90:93]
	v_mfma_f32_16x16x32_bf16 v[82:85], v[130:133], v[166:169], v[82:85]
	v_mfma_f32_16x16x32_bf16 v[74:77], v[138:141], v[166:169], v[74:77]
	v_mfma_f32_16x16x32_bf16 v[70:73], v[130:133], v[162:165], v[70:73]
	v_mfma_f32_16x16x32_bf16 v[66:69], v[138:141], v[162:165], v[66:69]
	v_mfma_f32_16x16x32_bf16 v[114:117], v[134:137], v[190:193], v[114:117]
	v_mfma_f32_16x16x32_bf16 v[106:109], v[142:145], v[190:193], v[106:109]
	v_mfma_f32_16x16x32_bf16 v[98:101], v[134:137], v[186:189], v[98:101]
	v_mfma_f32_16x16x32_bf16 v[90:93], v[142:145], v[186:189], v[90:93]
	v_mfma_f32_16x16x32_bf16 v[82:85], v[134:137], v[182:185], v[82:85]
	v_mfma_f32_16x16x32_bf16 v[74:77], v[142:145], v[182:185], v[74:77]
	v_mfma_f32_16x16x32_bf16 v[70:73], v[134:137], v[178:181], v[70:73]
	v_mfma_f32_16x16x32_bf16 v[66:69], v[142:145], v[178:181], v[66:69]
	s_barrier
	s_andn2_b64 s[42:43], exec, s[40:41]
	s_andn2_b64 vcc, exec, s[40:41]
	s_cbranch_vccnz .LBB0_1614
	ds_read_b128 v[174:177], v233 offset:16384
	ds_read_b128 v[190:193], v233 offset:17408
	ds_read_b128 v[170:173], v233 offset:18432
	ds_read_b128 v[186:189], v233 offset:19456
	ds_read_b128 v[166:169], v233 offset:20480
	ds_read_b128 v[182:185], v233 offset:21504
	ds_read_b128 v[162:165], v233 offset:22528
	ds_read_b128 v[178:181], v233 offset:23552
.LBB0_1614:
	s_add_u32 s50, s46, s48
	s_addc_u32 s51, s47, s49
	s_add_u32 s52, s50, 0x440000
	s_addc_u32 s53, s51, 0
	s_cmp_eq_u32 s48, 0x3fc0000
	s_cselect_b64 s[56:57], -1, 0
	s_and_b64 s[50:51], s[56:57], exec
	s_cselect_b32 s51, s31, s61
	s_cselect_b32 s50, s35, s60
	s_mov_b32 m0, s10
	s_cselect_b32 s53, s19, s53
	s_cselect_b32 s52, s20, s52
	s_add_u32 s68, s50, 0x4000
	global_load_lds_dwordx4 v194, s[50:51]
	s_mov_b32 m0, s11
	s_addc_u32 s69, s51, 0
	global_load_lds_dwordx4 v196, s[50:51]
	s_mov_b32 m0, s12
	s_and_b64 vcc, exec, s[42:43]
	global_load_lds_dwordx4 v194, s[68:69]
	s_mov_b32 m0, s13
	s_nop 0
	global_load_lds_dwordx4 v196, s[68:69]
	s_mov_b64 s[98:99], s[52:53]
	s_waitcnt vmcnt(6) lgkmcnt(0)
	s_barrier
	s_cbranch_vccnz .LBB0_1616
	s_waitcnt lgkmcnt(0)
	v_mfma_f32_16x16x32_bf16 v[62:65], v[146:149], v[174:177], v[62:65]
	v_mfma_f32_16x16x32_bf16 v[58:61], v[154:157], v[174:177], v[58:61]
	v_mfma_f32_16x16x32_bf16 v[46:49], v[146:149], v[170:173], v[46:49]
	v_mfma_f32_16x16x32_bf16 v[42:45], v[154:157], v[170:173], v[42:45]
	v_mfma_f32_16x16x32_bf16 v[30:33], v[146:149], v[166:169], v[30:33]
	v_mfma_f32_16x16x32_bf16 v[26:29], v[154:157], v[166:169], v[26:29]
	v_mfma_f32_16x16x32_bf16 v[14:17], v[146:149], v[162:165], v[14:17]
	v_mfma_f32_16x16x32_bf16 v[10:13], v[154:157], v[162:165], v[10:13]
	v_mfma_f32_16x16x32_bf16 v[62:65], v[150:153], v[190:193], v[62:65]
	v_mfma_f32_16x16x32_bf16 v[58:61], v[158:161], v[190:193], v[58:61]
	v_mfma_f32_16x16x32_bf16 v[46:49], v[150:153], v[186:189], v[46:49]
	v_mfma_f32_16x16x32_bf16 v[42:45], v[158:161], v[186:189], v[42:45]
	v_mfma_f32_16x16x32_bf16 v[30:33], v[150:153], v[182:185], v[30:33]
	v_mfma_f32_16x16x32_bf16 v[26:29], v[158:161], v[182:185], v[26:29]
	v_mfma_f32_16x16x32_bf16 v[14:17], v[150:153], v[178:181], v[14:17]
	v_mfma_f32_16x16x32_bf16 v[10:13], v[158:161], v[178:181], v[10:13]
	v_mfma_f32_16x16x32_bf16 v[54:57], v[130:133], v[174:177], v[54:57]
	v_mfma_f32_16x16x32_bf16 v[50:53], v[138:141], v[174:177], v[50:53]
	v_mfma_f32_16x16x32_bf16 v[38:41], v[130:133], v[170:173], v[38:41]
	v_mfma_f32_16x16x32_bf16 v[34:37], v[138:141], v[170:173], v[34:37]
	v_mfma_f32_16x16x32_bf16 v[22:25], v[130:133], v[166:169], v[22:25]
	v_mfma_f32_16x16x32_bf16 v[18:21], v[138:141], v[166:169], v[18:21]
	v_mfma_f32_16x16x32_bf16 v[6:9], v[130:133], v[162:165], v[6:9]
	v_mfma_f32_16x16x32_bf16 v[2:5], v[138:141], v[162:165], v[2:5]
	v_mfma_f32_16x16x32_bf16 v[54:57], v[134:137], v[190:193], v[54:57]
	v_mfma_f32_16x16x32_bf16 v[50:53], v[142:145], v[190:193], v[50:53]
	v_mfma_f32_16x16x32_bf16 v[38:41], v[134:137], v[186:189], v[38:41]
	v_mfma_f32_16x16x32_bf16 v[34:37], v[142:145], v[186:189], v[34:37]
	v_mfma_f32_16x16x32_bf16 v[22:25], v[134:137], v[182:185], v[22:25]
	v_mfma_f32_16x16x32_bf16 v[18:21], v[142:145], v[182:185], v[18:21]
	v_mfma_f32_16x16x32_bf16 v[6:9], v[134:137], v[178:181], v[6:9]
	v_mfma_f32_16x16x32_bf16 v[2:5], v[142:145], v[178:181], v[2:5]
.LBB0_1616:
	s_and_b64 vcc, s[38:39], s[56:57]
	v_cndmask_b32_e64 v131, v225, 0, vcc
	v_cndmask_b32_e32 v130, v224, v198, vcc
	v_lshl_add_u64 v[236:237], s[52:53], 0, v[130:131]
	s_barrier
	s_mov_b32 m0, s9
	s_nop 0
	global_load_lds_dwordx4 v194, s[98:99]
	s_mov_b32 m0, s14
	s_nop 0
	global_load_lds_dwordx4 v196, s[98:99]
	v_add_u32_e32 v1, 0x18000, v232
	ds_read_b128 v[146:149], v1
	ds_read_b128 v[150:153], v1 offset:1024
	ds_read_b128 v[154:157], v1 offset:2048
	ds_read_b128 v[158:161], v1 offset:3072
	v_add_u32_e32 v1, 0x1c000, v232
	ds_read_b128 v[130:133], v1
	ds_read_b128 v[134:137], v1 offset:1024
	ds_read_b128 v[138:141], v1 offset:2048
	ds_read_b128 v[142:145], v1 offset:3072
	s_mov_b32 m0, s15
	v_lshl_add_u64 v[238:239], v[236:237], 0, v[194:195]
	s_waitcnt lgkmcnt(0)
	ds_read_b128 v[174:177], v233 offset:32768
	ds_read_b128 v[190:193], v233 offset:33792
	ds_read_b128 v[170:173], v233 offset:34816
	ds_read_b128 v[186:189], v233 offset:35840
	ds_read_b128 v[166:169], v233 offset:36864
	ds_read_b128 v[182:185], v233 offset:37888
	ds_read_b128 v[162:165], v233 offset:38912
	ds_read_b128 v[178:181], v233 offset:39936
	global_load_lds_dwordx4 v[238:239], off
	v_lshl_add_u64 v[236:237], v[236:237], 0, v[196:197]
	s_mov_b32 m0, s16
	s_nop 0
	global_load_lds_dwordx4 v[236:237], off
	s_waitcnt vmcnt(8) lgkmcnt(0)
	s_barrier
	v_mfma_f32_16x16x32_bf16 v[126:129], v[146:149], v[174:177], v[126:129]
	v_mfma_f32_16x16x32_bf16 v[122:125], v[154:157], v[174:177], v[122:125]
	v_mfma_f32_16x16x32_bf16 v[118:121], v[146:149], v[170:173], v[118:121]
	v_mfma_f32_16x16x32_bf16 v[110:113], v[154:157], v[170:173], v[110:113]
	v_mfma_f32_16x16x32_bf16 v[102:105], v[146:149], v[166:169], v[102:105]
	v_mfma_f32_16x16x32_bf16 v[94:97], v[154:157], v[166:169], v[94:97]
	v_mfma_f32_16x16x32_bf16 v[86:89], v[146:149], v[162:165], v[86:89]
	v_mfma_f32_16x16x32_bf16 v[78:81], v[154:157], v[162:165], v[78:81]
	v_mfma_f32_16x16x32_bf16 v[126:129], v[150:153], v[190:193], v[126:129]
	v_mfma_f32_16x16x32_bf16 v[122:125], v[158:161], v[190:193], v[122:125]
	v_mfma_f32_16x16x32_bf16 v[118:121], v[150:153], v[186:189], v[118:121]
	v_mfma_f32_16x16x32_bf16 v[110:113], v[158:161], v[186:189], v[110:113]
	v_mfma_f32_16x16x32_bf16 v[102:105], v[150:153], v[182:185], v[102:105]
	v_mfma_f32_16x16x32_bf16 v[94:97], v[158:161], v[182:185], v[94:97]
	v_mfma_f32_16x16x32_bf16 v[86:89], v[150:153], v[178:181], v[86:89]
	v_mfma_f32_16x16x32_bf16 v[78:81], v[158:161], v[178:181], v[78:81]
	v_mfma_f32_16x16x32_bf16 v[114:117], v[130:133], v[174:177], v[114:117]
	v_mfma_f32_16x16x32_bf16 v[106:109], v[138:141], v[174:177], v[106:109]
	v_mfma_f32_16x16x32_bf16 v[98:101], v[130:133], v[170:173], v[98:101]
	v_mfma_f32_16x16x32_bf16 v[90:93], v[138:141], v[170:173], v[90:93]
	v_mfma_f32_16x16x32_bf16 v[82:85], v[130:133], v[166:169], v[82:85]
	v_mfma_f32_16x16x32_bf16 v[74:77], v[138:141], v[166:169], v[74:77]
	v_mfma_f32_16x16x32_bf16 v[70:73], v[130:133], v[162:165], v[70:73]
	v_mfma_f32_16x16x32_bf16 v[66:69], v[138:141], v[162:165], v[66:69]
	v_mfma_f32_16x16x32_bf16 v[114:117], v[134:137], v[190:193], v[114:117]
	v_mfma_f32_16x16x32_bf16 v[106:109], v[142:145], v[190:193], v[106:109]
	v_mfma_f32_16x16x32_bf16 v[98:101], v[134:137], v[186:189], v[98:101]
	v_mfma_f32_16x16x32_bf16 v[90:93], v[142:145], v[186:189], v[90:93]
	v_mfma_f32_16x16x32_bf16 v[82:85], v[134:137], v[182:185], v[82:85]
	v_mfma_f32_16x16x32_bf16 v[74:77], v[142:145], v[182:185], v[74:77]
	v_mfma_f32_16x16x32_bf16 v[70:73], v[134:137], v[178:181], v[70:73]
	v_mfma_f32_16x16x32_bf16 v[66:69], v[142:145], v[178:181], v[66:69]
	s_barrier
	s_and_b64 vcc, exec, s[42:43]
	s_cbranch_vccnz .LBB0_1618
	ds_read_b128 v[174:177], v233 offset:49152
	ds_read_b128 v[190:193], v233 offset:50176
	ds_read_b128 v[170:173], v233 offset:51200
	ds_read_b128 v[186:189], v233 offset:52224
	ds_read_b128 v[166:169], v233 offset:53248
	ds_read_b128 v[182:185], v233 offset:54272
	ds_read_b128 v[162:165], v233 offset:55296
	ds_read_b128 v[178:181], v233 offset:56320
.LBB0_1618:
	s_add_u32 s56, s50, 0x40000
	s_addc_u32 s57, s51, 0
	s_add_u32 s52, s52, 0x220000
	s_addc_u32 s53, s53, 0
	s_mov_b32 m0, s17
	s_add_u32 s50, s50, 0x44000
	global_load_lds_dwordx4 v194, s[56:57]
	s_mov_b32 m0, s29
	s_addc_u32 s51, s51, 0
	global_load_lds_dwordx4 v196, s[56:57]
	s_mov_b32 m0, s58
	s_and_b64 vcc, exec, s[42:43]
	global_load_lds_dwordx4 v194, s[50:51]
	s_mov_b32 m0, s59
	s_nop 0
	global_load_lds_dwordx4 v196, s[50:51]
	s_mov_b64 s[100:101], s[52:53]
	s_waitcnt vmcnt(6) lgkmcnt(0)
	s_barrier
	s_cbranch_vccnz .LBB0_1611
	s_waitcnt lgkmcnt(0)
	v_mfma_f32_16x16x32_bf16 v[62:65], v[146:149], v[174:177], v[62:65]
	v_mfma_f32_16x16x32_bf16 v[58:61], v[154:157], v[174:177], v[58:61]
	v_mfma_f32_16x16x32_bf16 v[46:49], v[146:149], v[170:173], v[46:49]
	v_mfma_f32_16x16x32_bf16 v[42:45], v[154:157], v[170:173], v[42:45]
	v_mfma_f32_16x16x32_bf16 v[30:33], v[146:149], v[166:169], v[30:33]
	v_mfma_f32_16x16x32_bf16 v[26:29], v[154:157], v[166:169], v[26:29]
	v_mfma_f32_16x16x32_bf16 v[14:17], v[146:149], v[162:165], v[14:17]
	v_mfma_f32_16x16x32_bf16 v[10:13], v[154:157], v[162:165], v[10:13]
	v_mfma_f32_16x16x32_bf16 v[62:65], v[150:153], v[190:193], v[62:65]
	v_mfma_f32_16x16x32_bf16 v[58:61], v[158:161], v[190:193], v[58:61]
	v_mfma_f32_16x16x32_bf16 v[46:49], v[150:153], v[186:189], v[46:49]
	v_mfma_f32_16x16x32_bf16 v[42:45], v[158:161], v[186:189], v[42:45]
	v_mfma_f32_16x16x32_bf16 v[30:33], v[150:153], v[182:185], v[30:33]
	v_mfma_f32_16x16x32_bf16 v[26:29], v[158:161], v[182:185], v[26:29]
	v_mfma_f32_16x16x32_bf16 v[14:17], v[150:153], v[178:181], v[14:17]
	v_mfma_f32_16x16x32_bf16 v[10:13], v[158:161], v[178:181], v[10:13]
	v_mfma_f32_16x16x32_bf16 v[54:57], v[130:133], v[174:177], v[54:57]
	v_mfma_f32_16x16x32_bf16 v[50:53], v[138:141], v[174:177], v[50:53]
	v_mfma_f32_16x16x32_bf16 v[38:41], v[130:133], v[170:173], v[38:41]
	v_mfma_f32_16x16x32_bf16 v[34:37], v[138:141], v[170:173], v[34:37]
	v_mfma_f32_16x16x32_bf16 v[22:25], v[130:133], v[166:169], v[22:25]
	v_mfma_f32_16x16x32_bf16 v[18:21], v[138:141], v[166:169], v[18:21]
	v_mfma_f32_16x16x32_bf16 v[6:9], v[130:133], v[162:165], v[6:9]
	v_mfma_f32_16x16x32_bf16 v[2:5], v[138:141], v[162:165], v[2:5]
	v_mfma_f32_16x16x32_bf16 v[54:57], v[134:137], v[190:193], v[54:57]
	v_mfma_f32_16x16x32_bf16 v[50:53], v[142:145], v[190:193], v[50:53]
	v_mfma_f32_16x16x32_bf16 v[38:41], v[134:137], v[186:189], v[38:41]
	v_mfma_f32_16x16x32_bf16 v[34:37], v[142:145], v[186:189], v[34:37]
	v_mfma_f32_16x16x32_bf16 v[22:25], v[134:137], v[182:185], v[22:25]
	v_mfma_f32_16x16x32_bf16 v[18:21], v[142:145], v[182:185], v[18:21]
	v_mfma_f32_16x16x32_bf16 v[6:9], v[134:137], v[178:181], v[6:9]
	v_mfma_f32_16x16x32_bf16 v[2:5], v[142:145], v[178:181], v[2:5]
	s_branch .LBB0_1611
